# static s_setprio 1 for waves 4-7 through each GEMM phase, per-block priority flips deleted
# speedup vs baseline: 1.0079x; 1.0061x over previous
; #define PG8_STAGE(bufoff, gbase, voff) do { _Pragma("unroll") for (int _i = 0; _i < 2; ++_i) \
;         __builtin_amdgcn_global_load_lds((const unsigned*)((const char*)(gbase) + (voff)[_i]), (PG8_LAS unsigned*)(lds + (bufoff) + ldsw + _i * 8192), 16, 0, 0); } while (0)
; #define PG8_BAR __builtin_amdgcn_s_barrier()
; template <class Epi, class Sched, bool ALIGN_EPI = false, bool SP2 = false>
; __device__ __forceinline__ void gemm_phase(PG8_LAS unsigned char* lds, const Gemm g, const Sched& S, const Epi& E) {
;     int tid = threadIdx.x; asm volatile("" : "+v"(tid));
;     const int wid = __builtin_amdgcn_readfirstlane(tid >> 6), lane = tid & 63, wr = wid >> 2, wc = wid & 3, fr = lane & 15, fq = lane >> 4;
;     const int K = g.K, nt = K / BK;
;     unsigned voffA[2], voffB[2];
; #pragma unroll
;     for (int i = 0; i < 2; ++i) { int R, C; stage_rc(tid * 16 + i * 8192, R, C); const int Rb = Epi::PERM ? ((R & ~31) + perm32(R & 31)) : R;
;         voffA[i] = (unsigned)(R * K + C) * 2u; voffB[i] = (unsigned)(Rb * K + C) * 2u; }
;     const size_t kstep = (size_t)(BK * 2);
;     const size_t hstep = (size_t)HALF * K * 2;
;     const size_t tstep = 2 * hstep;
;     const unsigned ldsw = (unsigned)wid * 1024u;
;     const int aoff = lds_byte(wr * 64 + fr, fq * 8), boff = lds_byte(wc * 32 + fr, fq * 8);
;     ...
;     Unit cur, nxt; int ui = 0;
;     if (!S.next(0, cur)) return;
;     f32x4 acc[2][2][4][2];
; #pragma unroll
;     for (int a = 0; a < 2; ++a)
; #pragma unroll
;         for (int b = 0; b < 2; ++b)
; #pragma unroll
;             for (int m = 0; m < 4; ++m)
; #pragma unroll
;                 for (int n = 0; n < 2; ++n) acc[a][b][m][n] = (f32x4){0.f, 0.f, 0.f, 0.f};
;     bf16x8 At[4][2], B0[2][2], B1[2][2];
;     const char* cA = (const char*)g.A + (size_t)cur.pm * tstep + (size_t)cur.kt0 * kstep; const char* cB = (const char*)g.Bt + (size_t)cur.pn * tstep + (size_t)cur.kt0 * kstep;
;     S.a_ready(cur);
;     if constexpr (SP2) {
;         PG8_STAGE(PG8_SB(0, 0), cB, voffB); PG8_STAGE(PG8_SB(0, 1), cB + hstep, voffB); PG8_STAGE(PG8_SA(0, 0), cA, voffA); PG8_STAGE(PG8_SA(0, 1), cA + hstep, voffA);
;         if (wr == 1) PG8_BAR;
;         PG8_WAIT_V(2); PG8_BAR;
;         PG8_STAGE(PG8_SB(1, 0), cB + kstep, voffB); PG8_STAGE(PG8_SA(1, 0), cA + kstep, voffA); PG8_STAGE(PG8_SB(1, 1), cB + hstep + kstep, voffB);
;         PG8_WAIT_V(6); PG8_BAR;
.LBB0_353:
	s_cmpk_lg_i32 s33, 0x100
	s_cselect_b64 s[16:17], -1, 0
	s_cmpk_eq_i32 s33, 0x100
	s_cselect_b64 s[54:55], -1, 0
	s_ashr_i32 s1, s33, 31
	s_and_b32 s5, s2, 7
	s_ashr_i32 s3, s2, 31
	v_writelane_b32 v255, s1, 10
	s_and_b32 s1, s2, 0x78
	s_or_b32 s4, s5, 4
	s_cmpk_lt_i32 s2, 0x80
	s_cselect_b32 s4, s5, s4
	s_or_b32 s1, s1, s4
	v_writelane_b32 v255, s5, 11
	s_andn2_b64 vcc, exec, s[6:7]
	s_or_b32 s51, s1, 0x700
	s_cbranch_vccnz .LBB0_608
	v_ashrrev_i32_e32 v2, 31, v11
	v_lshrrev_b32_e32 v2, 26, v2
	v_add_u32_e32 v2, v11, v2
	v_ashrrev_i32_e32 v10, 6, v2
	v_bfe_i32 v2, v11, 27, 1
	v_lshlrev_b32_e32 v1, 4, v11
	v_lshrrev_b32_e32 v2, 22, v2
	v_add_u32_e32 v2, v1, v2
	v_and_b32_e32 v2, 0xfffffc00, v2
	v_sub_u32_e32 v2, v1, v2
	v_lshrrev_b32_e32 v3, 4, v2
	v_bitop3_b32 v2, v3, v2, 32 bitop3:0x6c
	v_ashrrev_i32_e32 v4, 31, v2
	v_lshrrev_b32_e32 v4, 26, v4
	v_add_u32_e32 v4, v2, v4
	v_lshlrev_b32_e32 v3, 3, v10
	v_ashrrev_i32_e32 v12, 6, v4
	v_and_b32_e32 v4, 0xc0, v4
	v_and_b32_e32 v3, -16, v3
	v_sub_u32_e32 v2, v2, v4
	v_mov_b32_e32 v4, 1
	v_add_u32_e32 v3, v12, v3
	v_ashrrev_i16_sdwa v2, v4, sext(v2) dst_sel:DWORD dst_unused:UNUSED_PAD src0_sel:DWORD src1_sel:BYTE_0
	v_lshlrev_b32_e32 v5, 5, v10
	v_bfe_i32 v13, v2, 0, 16
	v_lshlrev_b32_e32 v2, 1, v3
	v_lshrrev_b32_e32 v6, 2, v3
	v_and_b32_e32 v7, 3, v12
	s_mov_b32 s4, 0x7ffe0
	v_and_b32_e32 v5, 32, v5
	v_and_b32_e32 v2, 24, v2
	v_and_b32_e32 v6, 4, v6
	v_and_or_b32 v7, v3, s4, v7
	v_or3_b32 v2, v7, v6, v2
	v_add_lshl_u32 v5, v5, v13, 1
	v_add_u32_e32 v1, 0x2000, v1
	v_lshl_add_u32 v144, v2, 13, v5
	v_ashrrev_i32_e32 v2, 31, v1
	v_lshrrev_b32_e32 v2, 22, v2
	v_add_u32_e32 v2, v1, v2
	v_ashrrev_i32_e32 v14, 10, v2
	v_mul_i32_i24_e32 v2, 0x400, v14
	v_sub_u32_e32 v1, v1, v2
	v_lshrrev_b32_e32 v2, 4, v1
	v_bitop3_b32 v1, v2, v1, 32 bitop3:0x6c
	v_lshl_add_u32 v142, v3, 13, v5
	v_ashrrev_i32_e32 v3, 31, v1
	v_lshrrev_b32_e32 v3, 26, v3
	v_writelane_b32 v255, s54, 12
	s_waitcnt lgkmcnt(0)
	s_add_u32 s53, s26, 0x14100000
	v_add_u32_e32 v3, v1, v3
	v_writelane_b32 v255, s55, 13
	s_addc_u32 s55, s27, 0
	v_lshlrev_b32_e32 v2, 3, v14
	v_ashrrev_i32_e32 v15, 6, v3
	v_and_b32_e32 v3, 0xc0, v3
	s_add_u32 s57, s26, 0x45900000
	v_and_b32_e32 v2, -16, v2
	v_sub_u32_e32 v1, v1, v3
	s_addc_u32 s65, s27, 0
	s_ashr_i32 s1, s0, 6
	v_add_u32_e32 v2, v15, v2
	v_ashrrev_i16_sdwa v1, v4, sext(v1) dst_sel:DWORD dst_unused:UNUSED_PAD src0_sel:DWORD src1_sel:BYTE_0
	v_and_b32_e32 v4, 3, v15
	s_ashr_i32 s79, s78, 31
	s_ashr_i32 s77, s76, 31
	v_and_or_b32 v4, v2, s4, v4
	s_ashr_i32 s4, s0, 8
	s_lshl_b32 s67, s1, 10
	s_lshl_b64 s[6:7], s[78:79], 21
	s_lshl_b64 s[8:9], s[76:77], 21
	s_add_u32 s12, s57, s8
	v_lshlrev_b32_e32 v5, 5, v14
	v_bfe_i32 v16, v1, 0, 16
	v_lshlrev_b32_e32 v1, 1, v2
	v_lshrrev_b32_e32 v3, 2, v2
	s_addc_u32 s13, s65, s9
	s_add_i32 s79, s67, 0
	v_and_b32_e32 v5, 32, v5
	v_and_b32_e32 v1, 24, v1
	v_and_b32_e32 v3, 4, v3
	s_add_i32 m0, s79, 0x10000
	v_or3_b32 v1, v4, v3, v1
	v_add_lshl_u32 v3, v5, v16, 1
	global_load_lds_dwordx4 v144, s[12:13]
	s_add_i32 m0, s79, 0x12000
	v_lshl_add_u32 v148, v1, 13, v3
	s_add_u32 s8, s12, 0x100000
	global_load_lds_dwordx4 v148, s[12:13]
	s_addc_u32 s9, s13, 0
	s_add_i32 m0, s79, 0x14000
	v_lshl_add_u32 v146, v2, 13, v3
	global_load_lds_dwordx4 v144, s[8:9]
	s_add_i32 m0, s79, 0x16000
	s_add_u32 s10, s53, s6
	s_addc_u32 s11, s55, s7
	s_add_i32 s88, s79, 0x2000
	global_load_lds_dwordx4 v148, s[8:9]
	s_mov_b32 m0, s79
	s_add_u32 s6, s10, 0x100000
	global_load_lds_dwordx4 v142, s[10:11]
	s_mov_b32 m0, s88
	s_addc_u32 s7, s11, 0
	s_add_i32 s89, s79, 0x4000
	global_load_lds_dwordx4 v146, s[10:11]
	s_mov_b32 m0, s89
	s_add_i32 s90, s79, 0x6000
	global_load_lds_dwordx4 v142, s[6:7]
	s_mov_b32 m0, s90
	v_mov_b32_e32 v151, 0
	global_load_lds_dwordx4 v146, s[6:7]
	v_mov_b32_e32 v145, v151
	v_mov_b32_e32 v149, v151
	v_mov_b32_e32 v143, v151
	v_mov_b32_e32 v147, v151
	s_cmp_eq_u32 s4, 1
	s_mov_b64 s[58:59], s[96:97]
	s_mov_b32 s91, 0
	v_lshl_add_u64 v[8:9], s[12:13], 0, v[144:145]
	v_lshl_add_u64 v[6:7], s[12:13], 0, v[148:149]
	v_lshl_add_u64 v[2:3], s[10:11], 0, v[142:143]
	s_cselect_b64 s[18:19], -1, 0
	s_cmp_lg_u32 s4, 1
	v_lshl_add_u64 v[4:5], s[10:11], 0, v[146:147]
	s_cbranch_scc1 .LBB0_356
	s_barrier
	s_setprio 1

; #define PG8_STAGE(bufoff, gbase, voff) do { _Pragma("unroll") for (int _i = 0; _i < 2; ++_i) \
;         __builtin_amdgcn_global_load_lds((const unsigned*)((const char*)(gbase) + (voff)[_i]), (PG8_LAS unsigned*)(lds + (bufoff) + ldsw + _i * 8192), 16, 0, 0); } while (0)
; #define PG8_LDA(dst, b, h) do { _Pragma("unroll") for (int m = 0; m < 4; ++m) _Pragma("unroll") for (int k = 0; k < 2; ++k) dst[m][k] = *(const PG8_LAS bf16x8*)(lds + PG8_SA(b, h) + aoff + m * 2048 + k * 1024); } while (0)
; #define PG8_LDB(dst, b, h) do { _Pragma("unroll") for (int n = 0; n < 2; ++n) _Pragma("unroll") for (int k = 0; k < 2; ++k) dst[n][k] = *(const PG8_LAS bf16x8*)(lds + PG8_SB(b, h) + boff + n * 2048 + k * 1024); } while (0)
; #define PG8_MMA(ai, bj, At, Bt) do { __builtin_amdgcn_s_setprio(1); _Pragma("unroll") for (int m = 0; m < 4; ++m) _Pragma("unroll") for (int n = 0; n < 2; ++n) _Pragma("unroll") for (int k = 0; k < 2; ++k) \
;         acc[ai][bj][m][n] = __builtin_amdgcn_mfma_f32_16x16x32_bf16(Bt[n][k], At[m][k], acc[ai][bj][m][n], 0, 0, 0); __builtin_amdgcn_s_setprio(0); } while (0)
; #define PG8_WAIT_V(n) asm volatile("s_waitcnt vmcnt(" #n ")" ::: "memory")
; #define PG8_WAIT_L(n) asm volatile("s_waitcnt lgkmcnt(" #n ")" ::: "memory")
; #define PG8_BAR __builtin_amdgcn_s_barrier()
; #define PG8_SCHED __builtin_amdgcn_sched_barrier(0)
; template <class Epi, class Sched, bool ALIGN_EPI = false, bool SP2 = false>
; __device__ __forceinline__ void gemm_phase(PG8_LAS unsigned char* lds, const Gemm g, const Sched& S, const Epi& E) {
;     ...
;             if constexpr (SP2) {
;             PG8_LDB(B0, 0, 0); PG8_LDB(B1, 0, 1); PG8_SCHED; PG8_LDA(At, 0, 0); PG8_STAGE(PG8_SA(1, 1), a1 + hstep, voffA);
;             PG8_WAIT_V(8); PG8_WAIT_L(0); PG8_BAR; PG8_MMA(0, 0, At, B0); PG8_MMA(0, 1, At, B1); PG8_BAR; PG8_SCHED;
;             PG8_LDA(At, 0, 1); PG8_STAGE(PG8_SB(0, 0), b2, voffB); PG8_STAGE(PG8_SB(0, 1), b2 + hstep, voffB); PG8_STAGE(PG8_SA(0, 0), a2, voffA);
;             PG8_WAIT_V(8); PG8_WAIT_L(0); PG8_BAR; PG8_MMA(1, 0, At, B0); PG8_MMA(1, 1, At, B1); PG8_BAR; PG8_SCHED;
.LBB0_366:
	ds_read_b128 v[130:133], v228
	ds_read_b128 v[134:137], v228 offset:1024
	ds_read_b128 v[138:141], v228 offset:2048
	ds_read_b128 v[170:173], v228 offset:3072
	ds_read_b128 v[174:177], v229
	ds_read_b128 v[178:181], v229 offset:1024
	ds_read_b128 v[182:185], v229 offset:2048
	ds_read_b128 v[186:189], v229 offset:3072
	s_add_u32 s12, s10, 0xfff00080
	s_addc_u32 s13, s11, -1
	s_cmp_eq_u32 s80, 60
	s_cselect_b32 s15, s0, s13
	s_cselect_b32 s14, s1, s12
	s_cselect_b32 s13, s61, s77
	s_cselect_b32 s12, s69, s71
	s_add_i32 m0, s79, 0xc000
	ds_read_b128 v[190:193], v230
	ds_read_b128 v[194:197], v230 offset:1024
	ds_read_b128 v[198:201], v230 offset:2048
	ds_read_b128 v[202:205], v230 offset:3072
	ds_read_b128 v[206:209], v230 offset:4096
	ds_read_b128 v[210:213], v230 offset:5120
	ds_read_b128 v[214:217], v230 offset:6144
	ds_read_b128 v[218:221], v230 offset:7168
	global_load_lds_dwordx4 v164, s[10:11]
	s_add_i32 m0, s79, 0xe000
	s_nop 0
	global_load_lds_dwordx4 v166, s[10:11]
	s_waitcnt vmcnt(8)
	s_waitcnt lgkmcnt(0)
	s_barrier
	s_waitcnt lgkmcnt(0)
	v_mfma_f32_16x16x32_bf16 v[126:129], v[130:133], v[190:193], v[126:129]
	v_mfma_f32_16x16x32_bf16 v[126:129], v[134:137], v[194:197], v[126:129]
	v_mfma_f32_16x16x32_bf16 v[122:125], v[138:141], v[190:193], v[122:125]
	v_mfma_f32_16x16x32_bf16 v[122:125], v[170:173], v[194:197], v[122:125]
	v_mfma_f32_16x16x32_bf16 v[110:113], v[130:133], v[198:201], v[110:113]
	v_mfma_f32_16x16x32_bf16 v[110:113], v[134:137], v[202:205], v[110:113]
	v_mfma_f32_16x16x32_bf16 v[106:109], v[138:141], v[198:201], v[106:109]
	v_mfma_f32_16x16x32_bf16 v[106:109], v[170:173], v[202:205], v[106:109]
	v_mfma_f32_16x16x32_bf16 v[94:97], v[130:133], v[206:209], v[94:97]
	v_mfma_f32_16x16x32_bf16 v[94:97], v[134:137], v[210:213], v[94:97]
	v_mfma_f32_16x16x32_bf16 v[90:93], v[138:141], v[206:209], v[90:93]
	v_mfma_f32_16x16x32_bf16 v[90:93], v[170:173], v[210:213], v[90:93]
	v_mfma_f32_16x16x32_bf16 v[78:81], v[130:133], v[214:217], v[78:81]
	v_mfma_f32_16x16x32_bf16 v[78:81], v[134:137], v[218:221], v[78:81]
	v_mfma_f32_16x16x32_bf16 v[74:77], v[138:141], v[214:217], v[74:77]
	v_mfma_f32_16x16x32_bf16 v[74:77], v[170:173], v[218:221], v[74:77]
	v_mfma_f32_16x16x32_bf16 v[118:121], v[174:177], v[190:193], v[118:121]
	v_mfma_f32_16x16x32_bf16 v[118:121], v[178:181], v[194:197], v[118:121]
	v_mfma_f32_16x16x32_bf16 v[114:117], v[182:185], v[190:193], v[114:117]
	v_mfma_f32_16x16x32_bf16 v[114:117], v[186:189], v[194:197], v[114:117]
	v_mfma_f32_16x16x32_bf16 v[102:105], v[174:177], v[198:201], v[102:105]
	v_mfma_f32_16x16x32_bf16 v[102:105], v[178:181], v[202:205], v[102:105]
	v_mfma_f32_16x16x32_bf16 v[98:101], v[182:185], v[198:201], v[98:101]
	v_mfma_f32_16x16x32_bf16 v[98:101], v[186:189], v[202:205], v[98:101]
	v_mfma_f32_16x16x32_bf16 v[86:89], v[174:177], v[206:209], v[86:89]
	v_mfma_f32_16x16x32_bf16 v[86:89], v[178:181], v[210:213], v[86:89]
	v_mfma_f32_16x16x32_bf16 v[82:85], v[182:185], v[206:209], v[82:85]
	v_mfma_f32_16x16x32_bf16 v[82:85], v[186:189], v[210:213], v[82:85]
	v_mfma_f32_16x16x32_bf16 v[70:73], v[174:177], v[214:217], v[70:73]
	v_mfma_f32_16x16x32_bf16 v[70:73], v[178:181], v[218:221], v[70:73]
	v_mfma_f32_16x16x32_bf16 v[66:69], v[182:185], v[214:217], v[66:69]
	v_mfma_f32_16x16x32_bf16 v[66:69], v[186:189], v[218:221], v[66:69]
	s_barrier
	s_add_i32 s81, s63, s67
	s_mov_b32 m0, s81
	ds_read_b128 v[190:193], v230 offset:16384
	ds_read_b128 v[194:197], v230 offset:17408
	ds_read_b128 v[198:201], v230 offset:18432
	ds_read_b128 v[202:205], v230 offset:19456
	ds_read_b128 v[206:209], v230 offset:20480
	ds_read_b128 v[210:213], v230 offset:21504
	ds_read_b128 v[214:217], v230 offset:22528
	ds_read_b128 v[218:221], v230 offset:23552
	global_load_lds_dwordx4 v144, s[12:13]
	s_add_i32 m0, s81, 0x2000
	s_add_u32 s82, s12, 0x100000
	s_addc_u32 s83, s13, 0
	s_add_i32 s81, s94, s67
	global_load_lds_dwordx4 v148, s[12:13]
	s_mov_b32 m0, s81
	s_nop 0
	global_load_lds_dwordx4 v144, s[82:83]
	s_add_i32 m0, s81, 0x2000
	s_nop 0
	global_load_lds_dwordx4 v148, s[82:83]
	s_mov_b32 m0, s79
	s_nop 0
	global_load_lds_dwordx4 v142, s[14:15]
	s_mov_b32 m0, s88
	s_nop 0
	global_load_lds_dwordx4 v146, s[14:15]
	s_waitcnt vmcnt(8)
	s_waitcnt lgkmcnt(0)
	s_barrier
	s_waitcnt lgkmcnt(0)
	v_mfma_f32_16x16x32_bf16 v[62:65], v[130:133], v[190:193], v[62:65]
	v_mfma_f32_16x16x32_bf16 v[62:65], v[134:137], v[194:197], v[62:65]
	v_mfma_f32_16x16x32_bf16 v[58:61], v[138:141], v[190:193], v[58:61]
	v_mfma_f32_16x16x32_bf16 v[58:61], v[170:173], v[194:197], v[58:61]
	v_mfma_f32_16x16x32_bf16 v[46:49], v[130:133], v[198:201], v[46:49]
	v_mfma_f32_16x16x32_bf16 v[46:49], v[134:137], v[202:205], v[46:49]
	v_mfma_f32_16x16x32_bf16 v[42:45], v[138:141], v[198:201], v[42:45]
	v_mfma_f32_16x16x32_bf16 v[42:45], v[170:173], v[202:205], v[42:45]
	v_mfma_f32_16x16x32_bf16 v[30:33], v[130:133], v[206:209], v[30:33]
	v_mfma_f32_16x16x32_bf16 v[30:33], v[134:137], v[210:213], v[30:33]
	v_mfma_f32_16x16x32_bf16 v[26:29], v[138:141], v[206:209], v[26:29]
	v_mfma_f32_16x16x32_bf16 v[26:29], v[170:173], v[210:213], v[26:29]
	v_mfma_f32_16x16x32_bf16 v[14:17], v[130:133], v[214:217], v[14:17]
	v_mfma_f32_16x16x32_bf16 v[14:17], v[134:137], v[218:221], v[14:17]
	v_mfma_f32_16x16x32_bf16 v[10:13], v[138:141], v[214:217], v[10:13]
	v_mfma_f32_16x16x32_bf16 v[10:13], v[170:173], v[218:221], v[10:13]
	v_mfma_f32_16x16x32_bf16 v[54:57], v[174:177], v[190:193], v[54:57]
	v_mfma_f32_16x16x32_bf16 v[54:57], v[178:181], v[194:197], v[54:57]
	v_mfma_f32_16x16x32_bf16 v[50:53], v[182:185], v[190:193], v[50:53]
	v_mfma_f32_16x16x32_bf16 v[50:53], v[186:189], v[194:197], v[50:53]
	v_mfma_f32_16x16x32_bf16 v[38:41], v[174:177], v[198:201], v[38:41]
	v_mfma_f32_16x16x32_bf16 v[38:41], v[178:181], v[202:205], v[38:41]
	v_mfma_f32_16x16x32_bf16 v[34:37], v[182:185], v[198:201], v[34:37]
	v_mfma_f32_16x16x32_bf16 v[34:37], v[186:189], v[202:205], v[34:37]
	v_mfma_f32_16x16x32_bf16 v[22:25], v[174:177], v[206:209], v[22:25]
	v_mfma_f32_16x16x32_bf16 v[22:25], v[178:181], v[210:213], v[22:25]
	v_mfma_f32_16x16x32_bf16 v[18:21], v[182:185], v[206:209], v[18:21]
	v_mfma_f32_16x16x32_bf16 v[18:21], v[186:189], v[210:213], v[18:21]
	v_mfma_f32_16x16x32_bf16 v[6:9], v[174:177], v[214:217], v[6:9]
	v_mfma_f32_16x16x32_bf16 v[6:9], v[178:181], v[218:221], v[6:9]
	v_mfma_f32_16x16x32_bf16 v[2:5], v[182:185], v[214:217], v[2:5]
	v_mfma_f32_16x16x32_bf16 v[2:5], v[186:189], v[218:221], v[2:5]
	s_barrier
; #define PG8_STAGE(bufoff, gbase, voff) do { _Pragma("unroll") for (int _i = 0; _i < 2; ++_i) \
;         __builtin_amdgcn_global_load_lds((const unsigned*)((const char*)(gbase) + (voff)[_i]), (PG8_LAS unsigned*)(lds + (bufoff) + ldsw + _i * 8192), 16, 0, 0); } while (0)
; #define PG8_LDA(dst, b, h) do { _Pragma("unroll") for (int m = 0; m < 4; ++m) _Pragma("unroll") for (int k = 0; k < 2; ++k) dst[m][k] = *(const PG8_LAS bf16x8*)(lds + PG8_SA(b, h) + aoff + m * 2048 + k * 1024); } while (0)
; #define PG8_WAIT_V(n) asm volatile("s_waitcnt vmcnt(" #n ")" ::: "memory")
; #define PG8_BAR __builtin_amdgcn_s_barrier()
; template <class Epi, class Sched, bool ALIGN_EPI = false, bool SP2 = false>
; __device__ __forceinline__ void gemm_phase(PG8_LAS unsigned char* lds, const Gemm g, const Sched& S, const Epi& E) {
;     ...
;         for (int t = 0; t < ntc; t += 2) {
;             if constexpr (Epi::MID) { if (ntc == nt && t == (nt >> 1)) E.mid(acc, cur, wr, wc, fr, fq); }
;             const bool last = (t == ntc - 2);
;             const char* a1 = cA + (size_t)(t + 1) * kstep;
;             const char* a2 = last ? nA : cA + (size_t)(t + 2) * kstep; const char* b2 = last ? nB : cB + (size_t)(t + 2) * kstep;
;             const char* a3 = a2 + kstep; const char* b3 = b2 + kstep;
;             if (last && has_next) S.a_ready(nxt);
;             if constexpr (SP2) {
;             PG8_LDB(B0, 0, 0); PG8_LDB(B1, 0, 1); PG8_SCHED; PG8_LDA(At, 0, 0); PG8_STAGE(PG8_SA(1, 1), a1 + hstep, voffA);
;             PG8_WAIT_V(8); PG8_WAIT_L(0); PG8_BAR; PG8_MMA(0, 0, At, B0); PG8_MMA(0, 1, At, B1); PG8_BAR; PG8_SCHED;
;             PG8_LDA(At, 0, 1); PG8_STAGE(PG8_SB(0, 0), b2, voffB); PG8_STAGE(PG8_SB(0, 1), b2 + hstep, voffB); PG8_STAGE(PG8_SA(0, 0), a2, voffA);
;             PG8_WAIT_V(8); PG8_WAIT_L(0); PG8_BAR; PG8_MMA(1, 0, At, B0); PG8_MMA(1, 1, At, B1); PG8_BAR; PG8_SCHED;
;             PG8_LDB(B0, 1, 0); PG8_LDB(B1, 1, 1); PG8_SCHED; PG8_LDA(At, 1, 0); PG8_STAGE(PG8_SA(0, 1), a2 + hstep, voffA);
;             PG8_WAIT_V(8); PG8_WAIT_L(0); PG8_BAR; PG8_MMA(0, 0, At, B0); PG8_MMA(0, 1, At, B1); PG8_BAR; PG8_SCHED;
;             PG8_LDA(At, 1, 1); PG8_STAGE(PG8_SB(1, 0), b3, voffB); PG8_STAGE(PG8_SB(1, 1), b3 + hstep, voffB); PG8_STAGE(PG8_SA(1, 0), a3, voffA);
;             PG8_WAIT_V(8); PG8_WAIT_L(0); PG8_BAR; PG8_MMA(1, 0, At, B0); PG8_MMA(1, 1, At, B1); PG8_BAR; PG8_SCHED;
	s_add_i32 s81, 0, 0x18000
	v_add_u32_e32 v150, s81, v153
	s_add_i32 s82, 0, 0x1c000
	ds_read_b128 v[130:133], v150
	ds_read_b128 v[134:137], v150 offset:1024
	ds_read_b128 v[138:141], v150 offset:2048
	ds_read_b128 v[170:173], v150 offset:3072
	v_add_u32_e32 v150, s82, v153
	ds_read_b128 v[174:177], v150
	ds_read_b128 v[178:181], v150 offset:1024
	ds_read_b128 v[182:185], v150 offset:2048
	ds_read_b128 v[186:189], v150 offset:3072
	s_add_u32 s14, s14, 0x100000
	s_addc_u32 s15, s15, 0
	s_mov_b32 m0, s89
	ds_read_b128 v[190:193], v230 offset:32768
	ds_read_b128 v[194:197], v230 offset:33792
	ds_read_b128 v[198:201], v230 offset:34816
	ds_read_b128 v[202:205], v230 offset:35840
	ds_read_b128 v[206:209], v230 offset:36864
	ds_read_b128 v[210:213], v230 offset:37888
	ds_read_b128 v[214:217], v230 offset:38912
	ds_read_b128 v[218:221], v230 offset:39936
	global_load_lds_dwordx4 v142, s[14:15]
	s_mov_b32 m0, s90
	s_nop 0
	global_load_lds_dwordx4 v146, s[14:15]
	s_waitcnt vmcnt(8)
	s_waitcnt lgkmcnt(0)
	s_barrier
	s_waitcnt lgkmcnt(0)
	v_mfma_f32_16x16x32_bf16 v[126:129], v[130:133], v[190:193], v[126:129]
	v_mfma_f32_16x16x32_bf16 v[126:129], v[134:137], v[194:197], v[126:129]
	v_mfma_f32_16x16x32_bf16 v[122:125], v[138:141], v[190:193], v[122:125]
	v_mfma_f32_16x16x32_bf16 v[122:125], v[170:173], v[194:197], v[122:125]
	v_mfma_f32_16x16x32_bf16 v[110:113], v[130:133], v[198:201], v[110:113]
	v_mfma_f32_16x16x32_bf16 v[110:113], v[134:137], v[202:205], v[110:113]
	v_mfma_f32_16x16x32_bf16 v[106:109], v[138:141], v[198:201], v[106:109]
	v_mfma_f32_16x16x32_bf16 v[106:109], v[170:173], v[202:205], v[106:109]
	v_mfma_f32_16x16x32_bf16 v[94:97], v[130:133], v[206:209], v[94:97]
	v_mfma_f32_16x16x32_bf16 v[94:97], v[134:137], v[210:213], v[94:97]
	v_mfma_f32_16x16x32_bf16 v[90:93], v[138:141], v[206:209], v[90:93]
	v_mfma_f32_16x16x32_bf16 v[90:93], v[170:173], v[210:213], v[90:93]
	v_mfma_f32_16x16x32_bf16 v[78:81], v[130:133], v[214:217], v[78:81]
	v_mfma_f32_16x16x32_bf16 v[78:81], v[134:137], v[218:221], v[78:81]
	v_mfma_f32_16x16x32_bf16 v[74:77], v[138:141], v[214:217], v[74:77]
	v_mfma_f32_16x16x32_bf16 v[74:77], v[170:173], v[218:221], v[74:77]
	v_mfma_f32_16x16x32_bf16 v[118:121], v[174:177], v[190:193], v[118:121]
	v_mfma_f32_16x16x32_bf16 v[118:121], v[178:181], v[194:197], v[118:121]
	v_mfma_f32_16x16x32_bf16 v[114:117], v[182:185], v[190:193], v[114:117]
	v_mfma_f32_16x16x32_bf16 v[114:117], v[186:189], v[194:197], v[114:117]
	v_mfma_f32_16x16x32_bf16 v[102:105], v[174:177], v[198:201], v[102:105]
	v_mfma_f32_16x16x32_bf16 v[102:105], v[178:181], v[202:205], v[102:105]
	v_mfma_f32_16x16x32_bf16 v[98:101], v[182:185], v[198:201], v[98:101]
	v_mfma_f32_16x16x32_bf16 v[98:101], v[186:189], v[202:205], v[98:101]
	v_mfma_f32_16x16x32_bf16 v[86:89], v[174:177], v[206:209], v[86:89]
	v_mfma_f32_16x16x32_bf16 v[86:89], v[178:181], v[210:213], v[86:89]
	v_mfma_f32_16x16x32_bf16 v[82:85], v[182:185], v[206:209], v[82:85]
	v_mfma_f32_16x16x32_bf16 v[82:85], v[186:189], v[210:213], v[82:85]
	v_mfma_f32_16x16x32_bf16 v[70:73], v[174:177], v[214:217], v[70:73]
	v_mfma_f32_16x16x32_bf16 v[70:73], v[178:181], v[218:221], v[70:73]
	v_mfma_f32_16x16x32_bf16 v[66:69], v[182:185], v[214:217], v[66:69]
	v_mfma_f32_16x16x32_bf16 v[66:69], v[186:189], v[218:221], v[66:69]
	s_barrier
	s_add_u32 s100, s14, 0xfff00080
	s_addc_u32 s101, s15, -1
	s_add_u32 s98, s12, 0x80
	s_addc_u32 s99, s13, 0
	s_add_i32 s14, s81, s67
	s_mov_b32 m0, s14
	ds_read_b128 v[190:193], v230 offset:49152
	ds_read_b128 v[194:197], v230 offset:50176
	ds_read_b128 v[198:201], v230 offset:51200
	ds_read_b128 v[202:205], v230 offset:52224
	ds_read_b128 v[206:209], v230 offset:53248
	ds_read_b128 v[210:213], v230 offset:54272
	ds_read_b128 v[214:217], v230 offset:55296
	ds_read_b128 v[218:221], v230 offset:56320
	global_load_lds_dwordx4 v144, s[98:99]
	s_add_i32 m0, s14, 0x2000
	s_add_u32 s12, s12, 0x100080
	s_addc_u32 s13, s13, 0
	s_add_i32 s14, s82, s67
	global_load_lds_dwordx4 v148, s[98:99]
	s_mov_b32 m0, s14
	s_nop 0
	global_load_lds_dwordx4 v144, s[12:13]
	s_add_i32 m0, s14, 0x2000
	s_nop 0
	global_load_lds_dwordx4 v148, s[12:13]
	s_mov_b32 m0, s93
	s_nop 0
	global_load_lds_dwordx4 v142, s[100:101]
	s_mov_b32 m0, s62
	s_nop 0
	global_load_lds_dwordx4 v146, s[100:101]
	s_waitcnt vmcnt(8)
	s_waitcnt lgkmcnt(0)
	s_barrier
	s_waitcnt lgkmcnt(0)
	v_mfma_f32_16x16x32_bf16 v[62:65], v[130:133], v[190:193], v[62:65]
	v_mfma_f32_16x16x32_bf16 v[62:65], v[134:137], v[194:197], v[62:65]
	v_mfma_f32_16x16x32_bf16 v[58:61], v[138:141], v[190:193], v[58:61]
	v_mfma_f32_16x16x32_bf16 v[58:61], v[170:173], v[194:197], v[58:61]
	v_mfma_f32_16x16x32_bf16 v[46:49], v[130:133], v[198:201], v[46:49]
	v_mfma_f32_16x16x32_bf16 v[46:49], v[134:137], v[202:205], v[46:49]
	v_mfma_f32_16x16x32_bf16 v[42:45], v[138:141], v[198:201], v[42:45]
	v_mfma_f32_16x16x32_bf16 v[42:45], v[170:173], v[202:205], v[42:45]
	v_mfma_f32_16x16x32_bf16 v[30:33], v[130:133], v[206:209], v[30:33]
	v_mfma_f32_16x16x32_bf16 v[30:33], v[134:137], v[210:213], v[30:33]
	v_mfma_f32_16x16x32_bf16 v[26:29], v[138:141], v[206:209], v[26:29]
	v_mfma_f32_16x16x32_bf16 v[26:29], v[170:173], v[210:213], v[26:29]
	v_mfma_f32_16x16x32_bf16 v[14:17], v[130:133], v[214:217], v[14:17]
	v_mfma_f32_16x16x32_bf16 v[14:17], v[134:137], v[218:221], v[14:17]
	v_mfma_f32_16x16x32_bf16 v[10:13], v[138:141], v[214:217], v[10:13]
	v_mfma_f32_16x16x32_bf16 v[10:13], v[170:173], v[218:221], v[10:13]
	v_mfma_f32_16x16x32_bf16 v[54:57], v[174:177], v[190:193], v[54:57]
	v_mfma_f32_16x16x32_bf16 v[54:57], v[178:181], v[194:197], v[54:57]
	v_mfma_f32_16x16x32_bf16 v[50:53], v[182:185], v[190:193], v[50:53]
	v_mfma_f32_16x16x32_bf16 v[50:53], v[186:189], v[194:197], v[50:53]
	v_mfma_f32_16x16x32_bf16 v[38:41], v[174:177], v[198:201], v[38:41]
	v_mfma_f32_16x16x32_bf16 v[38:41], v[178:181], v[202:205], v[38:41]
	v_mfma_f32_16x16x32_bf16 v[34:37], v[182:185], v[198:201], v[34:37]
	v_mfma_f32_16x16x32_bf16 v[34:37], v[186:189], v[202:205], v[34:37]
	v_mfma_f32_16x16x32_bf16 v[22:25], v[174:177], v[206:209], v[22:25]
	v_mfma_f32_16x16x32_bf16 v[22:25], v[178:181], v[210:213], v[22:25]
	v_mfma_f32_16x16x32_bf16 v[18:21], v[182:185], v[206:209], v[18:21]
	v_mfma_f32_16x16x32_bf16 v[18:21], v[186:189], v[210:213], v[18:21]
	v_mfma_f32_16x16x32_bf16 v[6:9], v[174:177], v[214:217], v[6:9]
	v_mfma_f32_16x16x32_bf16 v[6:9], v[178:181], v[218:221], v[6:9]
	v_mfma_f32_16x16x32_bf16 v[2:5], v[182:185], v[214:217], v[2:5]
	v_mfma_f32_16x16x32_bf16 v[2:5], v[186:189], v[218:221], v[2:5]
	s_barrier
	s_add_i32 s80, s80, 2
	s_add_u32 s10, s10, 0x100
	s_addc_u32 s11, s11, 0
	s_add_u32 s71, s71, 0x100
	s_addc_u32 s77, s77, 0
	s_cmp_gt_u32 s80, 61
	s_cbranch_scc0 .LBB0_366
	s_and_b64 vcc, exec, s[28:29]
	s_cbranch_vccz .LBB0_369
	s_barrier

; #define PG8_WAIT_V(n) asm volatile("s_waitcnt vmcnt(" #n ")" ::: "memory")
; #define PG8_BAR __builtin_amdgcn_s_barrier()
; template <class Epi, class Sched, bool ALIGN_EPI = false, bool SP2 = false>
; __device__ __forceinline__ void gemm_phase(PG8_LAS unsigned char* lds, const Gemm g, const Sched& S, const Epi& E) {
;     ...
;     PG8_WAIT_V(0);
;     if constexpr (!ALIGN_EPI) { if (wr == 0) PG8_BAR; }
;     PG8_BAR;
; __device__ __forceinline__ void xcd_barrier(const XcdBarrier& b) {
;     asm volatile("s_waitcnt vmcnt(0)" ::: "memory");
;     __syncthreads();
;     if (threadIdx.x == 0) {
;         unsigned* bar = b.bar;
;         __builtin_amdgcn_s_waitcnt(0);
;         unsigned nloc = b.st[0], nx = b.st[1];
;         if (nloc == 0u) { xcd_barrier_complete(bar, b.x, nloc, nx); b.st[0] = nloc; b.st[1] = nx; }
.LBB0_958:
	s_waitcnt vmcnt(0)
	s_setprio 0
	s_barrier
	s_mov_b64 s[0:1], exec
	v_readlane_b32 s4, v255, 7
	v_readlane_b32 s5, v255, 8
	s_and_b64 s[4:5], s[0:1], s[4:5]
	s_xor_b64 s[6:7], s[4:5], s[0:1]
	s_mov_b64 exec, s[4:5]
	s_cbranch_execz .LBB0_1013
	s_add_i32 s0, 0, 0x24020
	v_mov_b32_e32 v1, s0
	s_waitcnt vmcnt(0) expcnt(0) lgkmcnt(0)
	ds_read_b32 v3, v1
	s_add_i32 s0, 0, 0x24024
	v_mov_b32_e32 v1, s0
	ds_read_b32 v1, v1
	s_waitcnt lgkmcnt(1)
	v_cmp_ne_u32_e32 vcc, 0, v3
	s_cbranch_vccnz .LBB0_974
	v_readlane_b32 s4, v255, 2
	v_readlane_b32 s5, v255, 3
	s_load_dwordx2 s[0:1], s[4:5], 0x4
	v_readlane_b32 s4, v255, 0
	v_readlane_b32 s5, v255, 1
	s_add_u32 s8, s4, 0x4200
	s_addc_u32 s9, s5, 0
	s_add_u32 s10, s4, 0x4400
	s_addc_u32 s11, s5, 0
	s_add_u32 s12, s4, 0x4500
	s_addc_u32 s13, s5, 0
	s_add_u32 s14, s4, 0x4600
	s_addc_u32 s15, s5, 0
	s_add_u32 s16, s4, 0x4700
	s_addc_u32 s17, s5, 0
	s_add_u32 s18, s4, 0x4800
	s_addc_u32 s19, s5, 0
	s_add_u32 s20, s4, 0x4900
	s_addc_u32 s21, s5, 0
	s_add_u32 s22, s4, 0x4a00
	s_addc_u32 s23, s5, 0
	s_add_u32 s24, s4, 0x4b00
	s_addc_u32 s25, s5, 0
	s_add_u32 s26, s4, 0x4c00
	s_addc_u32 s27, s5, 0
	s_add_u32 s28, s4, 0x4d00
	s_addc_u32 s29, s5, 0
	s_add_u32 s30, s4, 0x4e00
	s_addc_u32 s31, s5, 0
	s_add_u32 s34, s4, 0x4f00
	s_addc_u32 s35, s5, 0
	s_add_u32 s36, s4, 0x5000
	s_addc_u32 s37, s5, 0
	s_add_u32 s38, s4, 0x5100
	s_addc_u32 s39, s5, 0
	s_add_u32 s40, s4, 0x5200
	s_addc_u32 s41, s5, 0
	s_waitcnt lgkmcnt(0)
	s_mul_i32 s0, s0, s33
	s_add_u32 s42, s4, 0x5300
	s_mul_i32 s0, s0, s1
	s_addc_u32 s43, s5, 0
	s_mov_b32 s1, 1
	v_mov_b32_e32 v17, 0
	s_branch .LBB0_962

; #define PG8_STAGE(bufoff, gbase, voff) do { _Pragma("unroll") for (int _i = 0; _i < 2; ++_i) \
;         __builtin_amdgcn_global_load_lds((const unsigned*)((const char*)(gbase) + (voff)[_i]), (PG8_LAS unsigned*)(lds + (bufoff) + ldsw + _i * 8192), 16, 0, 0); } while (0)
; #define PG8_BAR __builtin_amdgcn_s_barrier()
; template <class Epi, class Sched, bool ALIGN_EPI = false, bool SP2 = false>
; __device__ __forceinline__ void gemm_phase(PG8_LAS unsigned char* lds, const Gemm g, const Sched& S, const Epi& E) {
;     int tid = threadIdx.x; asm volatile("" : "+v"(tid));
;     const int wid = __builtin_amdgcn_readfirstlane(tid >> 6), lane = tid & 63, wr = wid >> 2, wc = wid & 3, fr = lane & 15, fq = lane >> 4;
;     const int K = g.K, nt = K / BK;
;     unsigned voffA[2], voffB[2];
; #pragma unroll
;     for (int i = 0; i < 2; ++i) { int R, C; stage_rc(tid * 16 + i * 8192, R, C); const int Rb = Epi::PERM ? ((R & ~31) + perm32(R & 31)) : R;
;         voffA[i] = (unsigned)(R * K + C) * 2u; voffB[i] = (unsigned)(Rb * K + C) * 2u; }
;     const size_t kstep = (size_t)(BK * 2);
;     const size_t hstep = (size_t)HALF * K * 2;
;     const size_t tstep = 2 * hstep;
;     const unsigned ldsw = (unsigned)wid * 1024u;
;     const int aoff = lds_byte(wr * 64 + fr, fq * 8), boff = lds_byte(wc * 32 + fr, fq * 8);
;     ...
;     Unit cur, nxt; int ui = 0;
;     if (!S.next(0, cur)) return;
;     f32x4 acc[2][2][4][2];
; #pragma unroll
;     for (int a = 0; a < 2; ++a)
; #pragma unroll
;         for (int b = 0; b < 2; ++b)
; #pragma unroll
;             for (int m = 0; m < 4; ++m)
; #pragma unroll
;                 for (int n = 0; n < 2; ++n) acc[a][b][m][n] = (f32x4){0.f, 0.f, 0.f, 0.f};
;     bf16x8 At[4][2], B0[2][2], B1[2][2];
;     const char* cA = (const char*)g.A + (size_t)cur.pm * tstep + (size_t)cur.kt0 * kstep; const char* cB = (const char*)g.Bt + (size_t)cur.pn * tstep + (size_t)cur.kt0 * kstep;
;     S.a_ready(cur);
;     if constexpr (SP2) {
;         PG8_STAGE(PG8_SB(0, 0), cB, voffB); PG8_STAGE(PG8_SB(0, 1), cB + hstep, voffB); PG8_STAGE(PG8_SA(0, 0), cA, voffA); PG8_STAGE(PG8_SA(0, 1), cA + hstep, voffA);
;         if (wr == 1) PG8_BAR;
;         PG8_WAIT_V(2); PG8_BAR;
;         PG8_STAGE(PG8_SB(1, 0), cB + kstep, voffB); PG8_STAGE(PG8_SA(1, 0), cA + kstep, voffA); PG8_STAGE(PG8_SB(1, 1), cB + hstep + kstep, voffB);
;         PG8_WAIT_V(6); PG8_BAR;
.LBB0_2469:
	s_andn2_b64 vcc, exec, s[14:15]
	s_cbranch_vccnz .LBB0_2518
	v_ashrrev_i32_e32 v2, 31, v3
	v_lshrrev_b32_e32 v2, 26, v2
	v_add_u32_e32 v2, v3, v2
	v_ashrrev_i32_e32 v12, 6, v2
	v_bfe_i32 v2, v3, 27, 1
	v_lshlrev_b32_e32 v1, 4, v3
	v_lshrrev_b32_e32 v2, 22, v2
	v_add_u32_e32 v2, v1, v2
	v_and_b32_e32 v2, 0xfffffc00, v2
	v_sub_u32_e32 v2, v1, v2
	v_lshrrev_b32_e32 v4, 4, v2
	v_bitop3_b32 v2, v4, v2, 32 bitop3:0x6c
	v_ashrrev_i32_e32 v5, 31, v2
	v_lshrrev_b32_e32 v5, 26, v5
	v_add_u32_e32 v5, v2, v5
	v_ashrrev_i32_e32 v13, 6, v5
	v_and_b32_e32 v5, 0xc0, v5
	v_sub_u32_e32 v2, v2, v5
	v_mov_b32_e32 v5, 1
	v_lshlrev_b32_e32 v4, 3, v12
	v_lshlrev_b32_e32 v6, 5, v12
	v_ashrrev_i16_sdwa v2, v5, sext(v2) dst_sel:DWORD dst_unused:UNUSED_PAD src0_sel:DWORD src1_sel:BYTE_0
	s_load_dwordx2 s[6:7], s[6:7], 0xe8
	v_and_b32_e32 v4, 0x7fff0, v4
	v_and_b32_e32 v6, 32, v6
	v_bfe_i32 v14, v2, 0, 16
	v_add_u32_e32 v2, v6, v14
	v_add_lshl_u32 v4, v13, v4, 13
	v_add_u32_e32 v1, 0x2000, v1
	v_lshl_add_u32 v134, v2, 1, v4
	v_ashrrev_i32_e32 v2, 31, v1
	v_lshrrev_b32_e32 v2, 22, v2
	v_add_u32_e32 v2, v1, v2
	s_waitcnt lgkmcnt(0)
	s_add_u32 s1, s6, 0x3d500000
	v_ashrrev_i32_e32 v15, 10, v2
	s_addc_u32 s28, s7, 0
	v_mul_i32_i24_e32 v2, 0x400, v15
	s_add_u32 s29, s6, 0x49300000
	v_sub_u32_e32 v1, v1, v2
	s_addc_u32 s54, s7, 0
	s_ashr_i32 s16, s20, 6
	v_lshrrev_b32_e32 v2, 4, v1
	s_ashr_i32 s13, s12, 31
	s_ashr_i32 s9, s8, 31
	s_ashr_i32 s11, s10, 31
	v_bitop3_b32 v1, v2, v1, 32 bitop3:0x6c
	s_ashr_i32 s17, s20, 8
	s_lshl_b32 s55, s16, 10
	s_lshl_b64 s[14:15], s[12:13], 21
	s_lshl_b64 s[18:19], s[8:9], 7
	s_lshl_b64 s[22:23], s[10:11], 21
	v_ashrrev_i32_e32 v4, 31, v1
	s_add_u32 s9, s29, s22
	v_lshrrev_b32_e32 v4, 26, v4
	s_addc_u32 s11, s54, s23
	v_add_u32_e32 v4, v1, v4
	s_add_u32 s46, s9, s18
	v_ashrrev_i32_e32 v16, 6, v4
	v_and_b32_e32 v4, 0xc0, v4
	s_addc_u32 s47, s11, s19
	s_add_i32 s11, s55, 0
	v_sub_u32_e32 v1, v1, v4
	s_add_i32 m0, s11, 0x10000
	v_lshlrev_b32_e32 v2, 3, v15
	v_lshlrev_b32_e32 v6, 5, v15
	v_ashrrev_i16_sdwa v1, v5, sext(v1) dst_sel:DWORD dst_unused:UNUSED_PAD src0_sel:DWORD src1_sel:BYTE_0
	global_load_lds_dwordx4 v134, s[46:47]
	s_add_i32 m0, s11, 0x12000
	v_and_b32_e32 v2, 0x7fff0, v2
	v_and_b32_e32 v6, 32, v6
	v_bfe_i32 v17, v1, 0, 16
	s_add_u32 s9, s1, s14
	v_add_u32_e32 v1, v6, v17
	v_add_lshl_u32 v2, v16, v2, 13
	s_addc_u32 s13, s28, s15
	v_lshl_add_u32 v136, v1, 1, v2
	s_add_u32 s14, s46, 0x100000
	global_load_lds_dwordx4 v136, s[46:47]
	s_addc_u32 s15, s47, 0
	s_add_i32 m0, s11, 0x14000
	v_mov_b32_e32 v2, 0
	global_load_lds_dwordx4 v134, s[14:15]
	s_add_i32 m0, s11, 0x16000
	s_add_u32 s42, s9, s18
	s_addc_u32 s43, s13, s19
	s_add_i32 s57, s11, 0x2000
	global_load_lds_dwordx4 v136, s[14:15]
	s_mov_b32 m0, s11
	s_add_u32 s14, s42, 0x100000
	global_load_lds_dwordx4 v134, s[42:43]
	s_mov_b32 m0, s57
	s_addc_u32 s15, s43, 0
	s_add_i32 s60, s11, 0x4000
	global_load_lds_dwordx4 v136, s[42:43]
	s_mov_b32 m0, s60
	s_add_i32 s61, s11, 0x6000
	global_load_lds_dwordx4 v134, s[14:15]
	s_mov_b32 m0, s61
	v_mov_b32_e32 v135, v2
	global_load_lds_dwordx4 v136, s[14:15]
	v_mov_b32_e32 v137, v2
	s_cmp_eq_u32 s17, 1
	s_mov_b32 s13, 0
	v_lshl_add_u64 v[10:11], s[46:47], 0, v[134:135]
	v_lshl_add_u64 v[8:9], s[46:47], 0, v[136:137]
	v_lshl_add_u64 v[4:5], s[42:43], 0, v[134:135]
	s_cselect_b64 s[14:15], -1, 0
	s_cmp_lg_u32 s17, 1
	v_lshl_add_u64 v[6:7], s[42:43], 0, v[136:137]
	s_cbranch_scc1 .LBB0_2472
	s_barrier
	s_setprio 1

; #define PG8_STAGE(bufoff, gbase, voff) do { _Pragma("unroll") for (int _i = 0; _i < 2; ++_i) \
;         __builtin_amdgcn_global_load_lds((const unsigned*)((const char*)(gbase) + (voff)[_i]), (PG8_LAS unsigned*)(lds + (bufoff) + ldsw + _i * 8192), 16, 0, 0); } while (0)
; #define PG8_LDA(dst, b, h) do { _Pragma("unroll") for (int m = 0; m < 4; ++m) _Pragma("unroll") for (int k = 0; k < 2; ++k) dst[m][k] = *(const PG8_LAS bf16x8*)(lds + PG8_SA(b, h) + aoff + m * 2048 + k * 1024); } while (0)
; #define PG8_LDB(dst, b, h) do { _Pragma("unroll") for (int n = 0; n < 2; ++n) _Pragma("unroll") for (int k = 0; k < 2; ++k) dst[n][k] = *(const PG8_LAS bf16x8*)(lds + PG8_SB(b, h) + boff + n * 2048 + k * 1024); } while (0)
; #define PG8_MMA(ai, bj, At, Bt) do { __builtin_amdgcn_s_setprio(1); _Pragma("unroll") for (int m = 0; m < 4; ++m) _Pragma("unroll") for (int n = 0; n < 2; ++n) _Pragma("unroll") for (int k = 0; k < 2; ++k) \
;         acc[ai][bj][m][n] = __builtin_amdgcn_mfma_f32_16x16x32_bf16(Bt[n][k], At[m][k], acc[ai][bj][m][n], 0, 0, 0); __builtin_amdgcn_s_setprio(0); } while (0)
; #define PG8_WAIT_V(n) asm volatile("s_waitcnt vmcnt(" #n ")" ::: "memory")
; #define PG8_WAIT_L(n) asm volatile("s_waitcnt lgkmcnt(" #n ")" ::: "memory")
; #define PG8_BAR __builtin_amdgcn_s_barrier()
; #define PG8_SCHED __builtin_amdgcn_sched_barrier(0)
; template <class Epi, class Sched, bool ALIGN_EPI = false, bool SP2 = false>
; __device__ __forceinline__ void gemm_phase(PG8_LAS unsigned char* lds, const Gemm g, const Sched& S, const Epi& E) {
;     ...
;             if constexpr (SP2) {
;             PG8_LDB(B0, 0, 0); PG8_LDB(B1, 0, 1); PG8_SCHED; PG8_LDA(At, 0, 0); PG8_STAGE(PG8_SA(1, 1), a1 + hstep, voffA);
;             PG8_WAIT_V(8); PG8_WAIT_L(0); PG8_BAR; PG8_MMA(0, 0, At, B0); PG8_MMA(0, 1, At, B1); PG8_BAR; PG8_SCHED;
;             PG8_LDA(At, 0, 1); PG8_STAGE(PG8_SB(0, 0), b2, voffB); PG8_STAGE(PG8_SB(0, 1), b2 + hstep, voffB); PG8_STAGE(PG8_SA(0, 0), a2, voffA);
;             PG8_WAIT_V(8); PG8_WAIT_L(0); PG8_BAR; PG8_MMA(1, 0, At, B0); PG8_MMA(1, 1, At, B1); PG8_BAR; PG8_SCHED;
.LBB0_2487:
	v_add_u32_e32 v3, s67, v183
	s_add_i32 s81, s50, 2
	ds_read_b128 v[154:157], v3
	ds_read_b128 v[158:161], v3 offset:1024
	ds_read_b128 v[162:165], v3 offset:2048
	ds_read_b128 v[166:169], v3 offset:3072
	v_add_u32_e32 v3, s68, v183
	s_add_u32 s51, s42, s46
	ds_read_b128 v[170:173], v3
	ds_read_b128 v[174:177], v3 offset:1024
	ds_read_b128 v[178:181], v3 offset:2048
	ds_read_b128 v[184:187], v3 offset:3072
	s_addc_u32 s52, s43, s47
	s_add_u32 s51, s51, 0x100
	s_addc_u32 s52, s52, 0
	s_add_u32 s82, s79, s46
	s_addc_u32 s83, s80, s47
	s_cmp_eq_u32 s9, s50
	s_cselect_b32 s53, s27, s52
	s_cselect_b32 s52, s35, s51
	s_cselect_b32 s51, s31, s83
	s_cselect_b32 s50, s78, s82
	v_lshl_add_u64 v[4:5], v[150:151], 0, s[46:47]
	s_add_i32 m0, s11, 0xc000
	ds_read_b128 v[188:191], v211
	ds_read_b128 v[192:195], v211 offset:1024
	ds_read_b128 v[196:199], v211 offset:2048
	ds_read_b128 v[200:203], v211 offset:3072
	ds_read_b128 v[204:207], v211 offset:4096
	ds_read_b128 v[212:215], v211 offset:5120
	ds_read_b128 v[216:219], v211 offset:6144
	ds_read_b128 v[220:223], v211 offset:7168
	global_load_lds_dwordx4 v[4:5], off
	v_lshl_add_u64 v[4:5], v[152:153], 0, s[46:47]
	s_add_i32 m0, s11, 0xe000
	s_nop 0
	global_load_lds_dwordx4 v[4:5], off
	s_waitcnt vmcnt(8)
	s_waitcnt lgkmcnt(0)
	s_barrier
	s_waitcnt lgkmcnt(0)
	v_mfma_f32_16x16x32_bf16 v[130:133], v[154:157], v[188:191], v[130:133]
	v_mfma_f32_16x16x32_bf16 v[130:133], v[158:161], v[192:195], v[130:133]
	v_mfma_f32_16x16x32_bf16 v[126:129], v[162:165], v[188:191], v[126:129]
	v_mfma_f32_16x16x32_bf16 v[126:129], v[166:169], v[192:195], v[126:129]
	v_mfma_f32_16x16x32_bf16 v[114:117], v[154:157], v[196:199], v[114:117]
	v_mfma_f32_16x16x32_bf16 v[114:117], v[158:161], v[200:203], v[114:117]
	v_mfma_f32_16x16x32_bf16 v[110:113], v[162:165], v[196:199], v[110:113]
	v_mfma_f32_16x16x32_bf16 v[110:113], v[166:169], v[200:203], v[110:113]
	v_mfma_f32_16x16x32_bf16 v[98:101], v[154:157], v[204:207], v[98:101]
	v_mfma_f32_16x16x32_bf16 v[98:101], v[158:161], v[212:215], v[98:101]
	v_mfma_f32_16x16x32_bf16 v[94:97], v[162:165], v[204:207], v[94:97]
	v_mfma_f32_16x16x32_bf16 v[94:97], v[166:169], v[212:215], v[94:97]
	v_mfma_f32_16x16x32_bf16 v[82:85], v[154:157], v[216:219], v[82:85]
	v_mfma_f32_16x16x32_bf16 v[82:85], v[158:161], v[220:223], v[82:85]
	v_mfma_f32_16x16x32_bf16 v[78:81], v[162:165], v[216:219], v[78:81]
	v_mfma_f32_16x16x32_bf16 v[78:81], v[166:169], v[220:223], v[78:81]
	v_mfma_f32_16x16x32_bf16 v[122:125], v[170:173], v[188:191], v[122:125]
	v_mfma_f32_16x16x32_bf16 v[122:125], v[174:177], v[192:195], v[122:125]
	v_mfma_f32_16x16x32_bf16 v[118:121], v[178:181], v[188:191], v[118:121]
	v_mfma_f32_16x16x32_bf16 v[118:121], v[184:187], v[192:195], v[118:121]
	v_mfma_f32_16x16x32_bf16 v[106:109], v[170:173], v[196:199], v[106:109]
	v_mfma_f32_16x16x32_bf16 v[106:109], v[174:177], v[200:203], v[106:109]
	v_mfma_f32_16x16x32_bf16 v[102:105], v[178:181], v[196:199], v[102:105]
	v_mfma_f32_16x16x32_bf16 v[102:105], v[184:187], v[200:203], v[102:105]
	v_mfma_f32_16x16x32_bf16 v[90:93], v[170:173], v[204:207], v[90:93]
	v_mfma_f32_16x16x32_bf16 v[90:93], v[174:177], v[212:215], v[90:93]
	v_mfma_f32_16x16x32_bf16 v[86:89], v[178:181], v[204:207], v[86:89]
	v_mfma_f32_16x16x32_bf16 v[86:89], v[184:187], v[212:215], v[86:89]
	v_mfma_f32_16x16x32_bf16 v[74:77], v[170:173], v[216:219], v[74:77]
	v_mfma_f32_16x16x32_bf16 v[74:77], v[174:177], v[220:223], v[74:77]
	v_mfma_f32_16x16x32_bf16 v[70:73], v[178:181], v[216:219], v[70:73]
	v_mfma_f32_16x16x32_bf16 v[70:73], v[184:187], v[220:223], v[70:73]
	s_barrier
	s_add_i32 s82, s67, s55
	s_mov_b32 m0, s82
	ds_read_b128 v[188:191], v211 offset:16384
	ds_read_b128 v[192:195], v211 offset:17408
	ds_read_b128 v[196:199], v211 offset:18432
	ds_read_b128 v[200:203], v211 offset:19456
	ds_read_b128 v[204:207], v211 offset:20480
	ds_read_b128 v[212:215], v211 offset:21504
	ds_read_b128 v[216:219], v211 offset:22528
	ds_read_b128 v[220:223], v211 offset:23552
	global_load_lds_dwordx4 v134, s[50:51]
	s_add_i32 m0, s82, 0x2000
	s_add_u32 s82, s50, 0x100000
	s_addc_u32 s83, s51, 0
	s_add_i32 s84, s68, s55
	global_load_lds_dwordx4 v136, s[50:51]
	s_mov_b32 m0, s84
	s_nop 0
	global_load_lds_dwordx4 v134, s[82:83]
	s_add_i32 m0, s84, 0x2000
	s_nop 0
	global_load_lds_dwordx4 v136, s[82:83]
	s_mov_b32 m0, s11
	s_nop 0
	global_load_lds_dwordx4 v134, s[52:53]
	s_mov_b32 m0, s57
	s_nop 0
	global_load_lds_dwordx4 v136, s[52:53]
	s_waitcnt vmcnt(8)
	s_waitcnt lgkmcnt(0)
	s_barrier
; #define PG8_STAGE(bufoff, gbase, voff) do { _Pragma("unroll") for (int _i = 0; _i < 2; ++_i) \
;         __builtin_amdgcn_global_load_lds((const unsigned*)((const char*)(gbase) + (voff)[_i]), (PG8_LAS unsigned*)(lds + (bufoff) + ldsw + _i * 8192), 16, 0, 0); } while (0)
; #define PG8_LDA(dst, b, h) do { _Pragma("unroll") for (int m = 0; m < 4; ++m) _Pragma("unroll") for (int k = 0; k < 2; ++k) dst[m][k] = *(const PG8_LAS bf16x8*)(lds + PG8_SA(b, h) + aoff + m * 2048 + k * 1024); } while (0)
; #define PG8_LDB(dst, b, h) do { _Pragma("unroll") for (int n = 0; n < 2; ++n) _Pragma("unroll") for (int k = 0; k < 2; ++k) dst[n][k] = *(const PG8_LAS bf16x8*)(lds + PG8_SB(b, h) + boff + n * 2048 + k * 1024); } while (0)
; #define PG8_MMA(ai, bj, At, Bt) do { __builtin_amdgcn_s_setprio(1); _Pragma("unroll") for (int m = 0; m < 4; ++m) _Pragma("unroll") for (int n = 0; n < 2; ++n) _Pragma("unroll") for (int k = 0; k < 2; ++k) \
;         acc[ai][bj][m][n] = __builtin_amdgcn_mfma_f32_16x16x32_bf16(Bt[n][k], At[m][k], acc[ai][bj][m][n], 0, 0, 0); __builtin_amdgcn_s_setprio(0); } while (0)
; #define PG8_WAIT_V(n) asm volatile("s_waitcnt vmcnt(" #n ")" ::: "memory")
; #define PG8_WAIT_L(n) asm volatile("s_waitcnt lgkmcnt(" #n ")" ::: "memory")
; #define PG8_BAR __builtin_amdgcn_s_barrier()
; template <class Epi, class Sched, bool ALIGN_EPI = false, bool SP2 = false>
; __device__ __forceinline__ void gemm_phase(PG8_LAS unsigned char* lds, const Gemm g, const Sched& S, const Epi& E) {
;     ...
;             PG8_WAIT_V(8); PG8_WAIT_L(0); PG8_BAR; PG8_MMA(0, 0, At, B0); PG8_MMA(0, 1, At, B1); PG8_BAR; PG8_SCHED;
;             PG8_LDA(At, 0, 1); PG8_STAGE(PG8_SB(0, 0), b2, voffB); PG8_STAGE(PG8_SB(0, 1), b2 + hstep, voffB); PG8_STAGE(PG8_SA(0, 0), a2, voffA);
;             PG8_WAIT_V(8); PG8_WAIT_L(0); PG8_BAR; PG8_MMA(1, 0, At, B0); PG8_MMA(1, 1, At, B1); PG8_BAR; PG8_SCHED;
;             PG8_LDB(B0, 1, 0); PG8_LDB(B1, 1, 1); PG8_SCHED; PG8_LDA(At, 1, 0); PG8_STAGE(PG8_SA(0, 1), a2 + hstep, voffA);
;             PG8_WAIT_V(8); PG8_WAIT_L(0); PG8_BAR; PG8_MMA(0, 0, At, B0); PG8_MMA(0, 1, At, B1); PG8_BAR; PG8_SCHED;
;             PG8_LDA(At, 1, 1); PG8_STAGE(PG8_SB(1, 0), b3, voffB); PG8_STAGE(PG8_SB(1, 1), b3 + hstep, voffB); PG8_STAGE(PG8_SA(1, 0), a3, voffA);
;             PG8_WAIT_V(8); PG8_WAIT_L(0); PG8_BAR; PG8_MMA(1, 0, At, B0); PG8_MMA(1, 1, At, B1); PG8_BAR; PG8_SCHED;
	s_waitcnt lgkmcnt(0)
	v_mfma_f32_16x16x32_bf16 v[66:69], v[154:157], v[188:191], v[66:69]
	v_mfma_f32_16x16x32_bf16 v[66:69], v[158:161], v[192:195], v[66:69]
	v_mfma_f32_16x16x32_bf16 v[62:65], v[162:165], v[188:191], v[62:65]
	v_mfma_f32_16x16x32_bf16 v[62:65], v[166:169], v[192:195], v[62:65]
	v_mfma_f32_16x16x32_bf16 v[50:53], v[154:157], v[196:199], v[50:53]
	v_mfma_f32_16x16x32_bf16 v[50:53], v[158:161], v[200:203], v[50:53]
	v_mfma_f32_16x16x32_bf16 v[46:49], v[162:165], v[196:199], v[46:49]
	v_mfma_f32_16x16x32_bf16 v[46:49], v[166:169], v[200:203], v[46:49]
	v_mfma_f32_16x16x32_bf16 v[34:37], v[154:157], v[204:207], v[34:37]
	v_mfma_f32_16x16x32_bf16 v[34:37], v[158:161], v[212:215], v[34:37]
	v_mfma_f32_16x16x32_bf16 v[30:33], v[162:165], v[204:207], v[30:33]
	v_mfma_f32_16x16x32_bf16 v[30:33], v[166:169], v[212:215], v[30:33]
	v_mfma_f32_16x16x32_bf16 v[18:21], v[154:157], v[216:219], v[18:21]
	v_mfma_f32_16x16x32_bf16 v[18:21], v[158:161], v[220:223], v[18:21]
	v_mfma_f32_16x16x32_bf16 v[14:17], v[162:165], v[216:219], v[14:17]
	v_mfma_f32_16x16x32_bf16 v[14:17], v[166:169], v[220:223], v[14:17]
	v_mfma_f32_16x16x32_bf16 v[58:61], v[170:173], v[188:191], v[58:61]
	v_mfma_f32_16x16x32_bf16 v[58:61], v[174:177], v[192:195], v[58:61]
	v_mfma_f32_16x16x32_bf16 v[54:57], v[178:181], v[188:191], v[54:57]
	v_mfma_f32_16x16x32_bf16 v[54:57], v[184:187], v[192:195], v[54:57]
	v_mfma_f32_16x16x32_bf16 v[42:45], v[170:173], v[196:199], v[42:45]
	v_mfma_f32_16x16x32_bf16 v[42:45], v[174:177], v[200:203], v[42:45]
	v_mfma_f32_16x16x32_bf16 v[38:41], v[178:181], v[196:199], v[38:41]
	v_mfma_f32_16x16x32_bf16 v[38:41], v[184:187], v[200:203], v[38:41]
	v_mfma_f32_16x16x32_bf16 v[26:29], v[170:173], v[204:207], v[26:29]
	v_mfma_f32_16x16x32_bf16 v[26:29], v[174:177], v[212:215], v[26:29]
	v_mfma_f32_16x16x32_bf16 v[22:25], v[178:181], v[204:207], v[22:25]
	v_mfma_f32_16x16x32_bf16 v[22:25], v[184:187], v[212:215], v[22:25]
	v_mfma_f32_16x16x32_bf16 v[10:13], v[170:173], v[216:219], v[10:13]
	v_mfma_f32_16x16x32_bf16 v[10:13], v[174:177], v[220:223], v[10:13]
	v_mfma_f32_16x16x32_bf16 v[4:7], v[178:181], v[216:219], v[6:9]
	v_mfma_f32_16x16x32_bf16 v[4:7], v[184:187], v[220:223], v[4:7]
	s_barrier
	s_add_i32 s82, 0, 0x18000
	v_add_u32_e32 v3, s82, v183
	s_add_i32 s83, 0, 0x1c000
	ds_read_b128 v[154:157], v3
	ds_read_b128 v[158:161], v3 offset:1024
	ds_read_b128 v[162:165], v3 offset:2048
	ds_read_b128 v[166:169], v3 offset:3072
	v_add_u32_e32 v3, s83, v183
	ds_read_b128 v[170:173], v3
	ds_read_b128 v[174:177], v3 offset:1024
	ds_read_b128 v[178:181], v3 offset:2048
	ds_read_b128 v[184:187], v3 offset:3072
	s_add_u32 s52, s52, 0x100000
	s_addc_u32 s53, s53, 0
	s_mov_b32 m0, s60
	ds_read_b128 v[188:191], v211 offset:32768
	ds_read_b128 v[192:195], v211 offset:33792
	ds_read_b128 v[196:199], v211 offset:34816
	ds_read_b128 v[200:203], v211 offset:35840
	ds_read_b128 v[204:207], v211 offset:36864
	ds_read_b128 v[212:215], v211 offset:37888
	ds_read_b128 v[216:219], v211 offset:38912
	ds_read_b128 v[220:223], v211 offset:39936
	global_load_lds_dwordx4 v134, s[52:53]
	s_mov_b32 m0, s61
	s_nop 0
	global_load_lds_dwordx4 v136, s[52:53]
	s_waitcnt vmcnt(8)
	s_waitcnt lgkmcnt(0)
	s_barrier
	s_waitcnt lgkmcnt(0)
	v_mfma_f32_16x16x32_bf16 v[130:133], v[154:157], v[188:191], v[130:133]
	v_mfma_f32_16x16x32_bf16 v[130:133], v[158:161], v[192:195], v[130:133]
	v_mfma_f32_16x16x32_bf16 v[126:129], v[162:165], v[188:191], v[126:129]
	v_mfma_f32_16x16x32_bf16 v[126:129], v[166:169], v[192:195], v[126:129]
	v_mfma_f32_16x16x32_bf16 v[114:117], v[154:157], v[196:199], v[114:117]
	v_mfma_f32_16x16x32_bf16 v[114:117], v[158:161], v[200:203], v[114:117]
	v_mfma_f32_16x16x32_bf16 v[110:113], v[162:165], v[196:199], v[110:113]
	v_mfma_f32_16x16x32_bf16 v[110:113], v[166:169], v[200:203], v[110:113]
	v_mfma_f32_16x16x32_bf16 v[98:101], v[154:157], v[204:207], v[98:101]
	v_mfma_f32_16x16x32_bf16 v[98:101], v[158:161], v[212:215], v[98:101]
	v_mfma_f32_16x16x32_bf16 v[94:97], v[162:165], v[204:207], v[94:97]
	v_mfma_f32_16x16x32_bf16 v[94:97], v[166:169], v[212:215], v[94:97]
	v_mfma_f32_16x16x32_bf16 v[82:85], v[154:157], v[216:219], v[82:85]
	v_mfma_f32_16x16x32_bf16 v[82:85], v[158:161], v[220:223], v[82:85]
	v_mfma_f32_16x16x32_bf16 v[78:81], v[162:165], v[216:219], v[78:81]
	v_mfma_f32_16x16x32_bf16 v[78:81], v[166:169], v[220:223], v[78:81]
	v_mfma_f32_16x16x32_bf16 v[122:125], v[170:173], v[188:191], v[122:125]
	v_mfma_f32_16x16x32_bf16 v[122:125], v[174:177], v[192:195], v[122:125]
	v_mfma_f32_16x16x32_bf16 v[118:121], v[178:181], v[188:191], v[118:121]
	v_mfma_f32_16x16x32_bf16 v[118:121], v[184:187], v[192:195], v[118:121]
	v_mfma_f32_16x16x32_bf16 v[106:109], v[170:173], v[196:199], v[106:109]
	v_mfma_f32_16x16x32_bf16 v[106:109], v[174:177], v[200:203], v[106:109]
	v_mfma_f32_16x16x32_bf16 v[102:105], v[178:181], v[196:199], v[102:105]
	v_mfma_f32_16x16x32_bf16 v[102:105], v[184:187], v[200:203], v[102:105]
	v_mfma_f32_16x16x32_bf16 v[90:93], v[170:173], v[204:207], v[90:93]
	v_mfma_f32_16x16x32_bf16 v[90:93], v[174:177], v[212:215], v[90:93]
	v_mfma_f32_16x16x32_bf16 v[86:89], v[178:181], v[204:207], v[86:89]
	v_mfma_f32_16x16x32_bf16 v[86:89], v[184:187], v[212:215], v[86:89]
	v_mfma_f32_16x16x32_bf16 v[74:77], v[170:173], v[216:219], v[74:77]
	v_mfma_f32_16x16x32_bf16 v[74:77], v[174:177], v[220:223], v[74:77]
	v_mfma_f32_16x16x32_bf16 v[70:73], v[178:181], v[216:219], v[70:73]
	v_mfma_f32_16x16x32_bf16 v[70:73], v[184:187], v[220:223], v[70:73]
	s_barrier
; #define PG8_STAGE(bufoff, gbase, voff) do { _Pragma("unroll") for (int _i = 0; _i < 2; ++_i) \
;         __builtin_amdgcn_global_load_lds((const unsigned*)((const char*)(gbase) + (voff)[_i]), (PG8_LAS unsigned*)(lds + (bufoff) + ldsw + _i * 8192), 16, 0, 0); } while (0)
; #define PG8_LDA(dst, b, h) do { _Pragma("unroll") for (int m = 0; m < 4; ++m) _Pragma("unroll") for (int k = 0; k < 2; ++k) dst[m][k] = *(const PG8_LAS bf16x8*)(lds + PG8_SA(b, h) + aoff + m * 2048 + k * 1024); } while (0)
; #define PG8_MMA(ai, bj, At, Bt) do { __builtin_amdgcn_s_setprio(1); _Pragma("unroll") for (int m = 0; m < 4; ++m) _Pragma("unroll") for (int n = 0; n < 2; ++n) _Pragma("unroll") for (int k = 0; k < 2; ++k) \
;         acc[ai][bj][m][n] = __builtin_amdgcn_mfma_f32_16x16x32_bf16(Bt[n][k], At[m][k], acc[ai][bj][m][n], 0, 0, 0); __builtin_amdgcn_s_setprio(0); } while (0)
; #define PG8_WAIT_V(n) asm volatile("s_waitcnt vmcnt(" #n ")" ::: "memory")
; #define PG8_WAIT_L(n) asm volatile("s_waitcnt lgkmcnt(" #n ")" ::: "memory")
; #define PG8_BAR __builtin_amdgcn_s_barrier()
; #define PG8_SCHED __builtin_amdgcn_sched_barrier(0)
; template <class Epi, class Sched, bool ALIGN_EPI = false, bool SP2 = false>
; __device__ __forceinline__ void gemm_phase(PG8_LAS unsigned char* lds, const Gemm g, const Sched& S, const Epi& E) {
;     ...
;             PG8_LDA(At, 1, 1); PG8_STAGE(PG8_SB(1, 0), b3, voffB); PG8_STAGE(PG8_SB(1, 1), b3 + hstep, voffB); PG8_STAGE(PG8_SA(1, 0), a3, voffA);
;             PG8_WAIT_V(8); PG8_WAIT_L(0); PG8_BAR; PG8_MMA(1, 0, At, B0); PG8_MMA(1, 1, At, B1); PG8_BAR; PG8_SCHED;
	s_add_u32 s100, s52, 0xfff00080
	s_addc_u32 s101, s53, -1
	s_add_u32 s98, s50, 0x80
	s_addc_u32 s99, s51, 0
	s_add_i32 s52, s82, s55
	s_mov_b32 m0, s52
	ds_read_b128 v[188:191], v211 offset:49152
	ds_read_b128 v[192:195], v211 offset:50176
	ds_read_b128 v[196:199], v211 offset:51200
	ds_read_b128 v[200:203], v211 offset:52224
	ds_read_b128 v[204:207], v211 offset:53248
	ds_read_b128 v[212:215], v211 offset:54272
	ds_read_b128 v[216:219], v211 offset:55296
	ds_read_b128 v[220:223], v211 offset:56320
	global_load_lds_dwordx4 v134, s[98:99]
	s_add_i32 m0, s52, 0x2000
	s_add_u32 s50, s50, 0x100080
	s_addc_u32 s51, s51, 0
	s_add_i32 s52, s83, s55
	global_load_lds_dwordx4 v136, s[98:99]
	s_mov_b32 m0, s52
	s_nop 0
	global_load_lds_dwordx4 v134, s[50:51]
	s_add_i32 m0, s52, 0x2000
	s_nop 0
	global_load_lds_dwordx4 v136, s[50:51]
	s_mov_b32 m0, s63
	s_nop 0
	global_load_lds_dwordx4 v134, s[100:101]
	s_mov_b32 m0, s64
	s_nop 0
	global_load_lds_dwordx4 v136, s[100:101]
	s_waitcnt vmcnt(8)
	s_waitcnt lgkmcnt(0)
	s_barrier
	s_waitcnt lgkmcnt(0)
	v_mfma_f32_16x16x32_bf16 v[66:69], v[154:157], v[188:191], v[66:69]
	v_mfma_f32_16x16x32_bf16 v[66:69], v[158:161], v[192:195], v[66:69]
	v_mfma_f32_16x16x32_bf16 v[62:65], v[162:165], v[188:191], v[62:65]
	v_mfma_f32_16x16x32_bf16 v[62:65], v[166:169], v[192:195], v[62:65]
	v_mfma_f32_16x16x32_bf16 v[50:53], v[154:157], v[196:199], v[50:53]
	v_mfma_f32_16x16x32_bf16 v[50:53], v[158:161], v[200:203], v[50:53]
	v_mfma_f32_16x16x32_bf16 v[46:49], v[162:165], v[196:199], v[46:49]
	v_mfma_f32_16x16x32_bf16 v[46:49], v[166:169], v[200:203], v[46:49]
	v_mfma_f32_16x16x32_bf16 v[34:37], v[154:157], v[204:207], v[34:37]
	v_mfma_f32_16x16x32_bf16 v[34:37], v[158:161], v[212:215], v[34:37]
	v_mfma_f32_16x16x32_bf16 v[30:33], v[162:165], v[204:207], v[30:33]
	v_mfma_f32_16x16x32_bf16 v[30:33], v[166:169], v[212:215], v[30:33]
	v_mfma_f32_16x16x32_bf16 v[18:21], v[154:157], v[216:219], v[18:21]
	v_mfma_f32_16x16x32_bf16 v[18:21], v[158:161], v[220:223], v[18:21]
	v_mfma_f32_16x16x32_bf16 v[14:17], v[162:165], v[216:219], v[14:17]
	v_mfma_f32_16x16x32_bf16 v[14:17], v[166:169], v[220:223], v[14:17]
	v_mfma_f32_16x16x32_bf16 v[58:61], v[170:173], v[188:191], v[58:61]
	v_mfma_f32_16x16x32_bf16 v[58:61], v[174:177], v[192:195], v[58:61]
	v_mfma_f32_16x16x32_bf16 v[54:57], v[178:181], v[188:191], v[54:57]
	v_mfma_f32_16x16x32_bf16 v[54:57], v[184:187], v[192:195], v[54:57]
	v_mfma_f32_16x16x32_bf16 v[42:45], v[170:173], v[196:199], v[42:45]
	v_mfma_f32_16x16x32_bf16 v[42:45], v[174:177], v[200:203], v[42:45]
	v_mfma_f32_16x16x32_bf16 v[38:41], v[178:181], v[196:199], v[38:41]
	v_mfma_f32_16x16x32_bf16 v[38:41], v[184:187], v[200:203], v[38:41]
	v_mfma_f32_16x16x32_bf16 v[26:29], v[170:173], v[204:207], v[26:29]
	v_mfma_f32_16x16x32_bf16 v[26:29], v[174:177], v[212:215], v[26:29]
	v_mfma_f32_16x16x32_bf16 v[22:25], v[178:181], v[204:207], v[22:25]
	v_mfma_f32_16x16x32_bf16 v[22:25], v[184:187], v[212:215], v[22:25]
	v_mfma_f32_16x16x32_bf16 v[8:11], v[170:173], v[216:219], v[10:13]
	v_mfma_f32_16x16x32_bf16 v[10:13], v[174:177], v[220:223], v[8:11]
	v_mfma_f32_16x16x32_bf16 v[4:7], v[178:181], v[216:219], v[4:7]
	v_mfma_f32_16x16x32_bf16 v[6:9], v[184:187], v[220:223], v[4:7]
	s_barrier
	s_add_u32 s46, s46, 0x100
	s_addc_u32 s47, s47, 0
	s_cmp_ge_i32 s81, s77
	s_cbranch_scc1 .LBB0_2489
	s_mov_b32 s50, s81
	s_branch .LBB0_2485

; #define PG8_WAIT_V(n) asm volatile("s_waitcnt vmcnt(" #n ")" ::: "memory")
; #define PG8_BAR __builtin_amdgcn_s_barrier()
; template <class Epi, class Sched, bool ALIGN_EPI = false, bool SP2 = false>
; __device__ __forceinline__ void gemm_phase(PG8_LAS unsigned char* lds, const Gemm g, const Sched& S, const Epi& E) {
;     ...
;     PG8_WAIT_V(0);
;     if constexpr (!ALIGN_EPI) { if (wr == 0) PG8_BAR; }
;     PG8_BAR;
; __device__ __forceinline__ void xcd_barrier(const XcdBarrier& b) {
;     asm volatile("s_waitcnt vmcnt(0)" ::: "memory");
;     __syncthreads();
;     if (threadIdx.x == 0) {
;         unsigned* bar = b.bar;
;         __builtin_amdgcn_s_waitcnt(0);
;         unsigned nloc = b.st[0], nx = b.st[1];
;         if (nloc == 0u) { xcd_barrier_complete(bar, b.x, nloc, nx); b.st[0] = nloc; b.st[1] = nx; }
.LBB0_2518:
	s_waitcnt vmcnt(0)
	s_waitcnt vmcnt(0) lgkmcnt(0)
	s_setprio 0
	s_barrier
	s_mov_b64 s[6:7], exec
	v_readlane_b32 s8, v255, 7
	v_readlane_b32 s9, v255, 8
	s_and_b64 s[8:9], s[6:7], s[8:9]
	s_xor_b64 s[6:7], s[8:9], s[6:7]
	s_mov_b64 exec, s[8:9]
	s_cbranch_execz .LBB0_2571
	s_add_i32 s1, 0, 0x24020
	v_mov_b32_e32 v1, s1
	s_waitcnt vmcnt(0) expcnt(0) lgkmcnt(0)
	ds_read_b32 v3, v1
	s_add_i32 s1, 0, 0x24024
	v_mov_b32_e32 v1, s1
	ds_read_b32 v1, v1
	s_waitcnt lgkmcnt(1)
	v_cmp_ne_u32_e32 vcc, 0, v3
	s_cbranch_vccnz .LBB0_2534
	v_readlane_b32 s8, v255, 2
	v_readlane_b32 s9, v255, 3
	s_load_dwordx2 s[12:13], s[8:9], 0x4
	v_readlane_b32 s28, v255, 0
	v_readlane_b32 s29, v255, 1
	s_add_u32 s8, s28, 0x4200
	s_addc_u32 s9, s29, 0
	s_add_u32 s10, s28, 0x4400
	s_addc_u32 s11, s29, 0
	s_waitcnt lgkmcnt(0)
	s_mul_i32 s1, s12, s33
	s_add_u32 s12, s28, 0x4500
	s_mul_i32 s1, s1, s13
	s_addc_u32 s13, s29, 0
	s_add_u32 s14, s28, 0x4600
	s_addc_u32 s15, s29, 0
	s_add_u32 s16, s28, 0x4700
	s_addc_u32 s17, s29, 0
	s_add_u32 s18, s28, 0x4800
	s_addc_u32 s19, s29, 0
	s_add_u32 s20, s28, 0x4900
	s_addc_u32 s21, s29, 0
	s_add_u32 s22, s28, 0x4a00
	s_addc_u32 s23, s29, 0
	s_add_u32 s24, s28, 0x4b00
	s_addc_u32 s25, s29, 0
	s_add_u32 s26, s28, 0x4c00
	s_addc_u32 s27, s29, 0
	s_add_u32 s30, s28, 0x4d00
	s_addc_u32 s31, s29, 0
	s_add_u32 s34, s28, 0x4e00
	s_addc_u32 s35, s29, 0
	s_add_u32 s36, s28, 0x4f00
	s_addc_u32 s37, s29, 0
	s_add_u32 s38, s28, 0x5000
	s_addc_u32 s39, s29, 0
	s_add_u32 s40, s28, 0x5100
	s_addc_u32 s41, s29, 0
	s_add_u32 s42, s28, 0x5200
	s_addc_u32 s43, s29, 0
	s_add_u32 s44, s28, 0x5300
	s_addc_u32 s45, s29, 0
	s_mov_b32 s28, 1
	v_mov_b32_e32 v17, 0
	s_branch .LBB0_2522

; #define PG8_STAGE(bufoff, gbase, voff) do { _Pragma("unroll") for (int _i = 0; _i < 2; ++_i) \
;         __builtin_amdgcn_global_load_lds((const unsigned*)((const char*)(gbase) + (voff)[_i]), (PG8_LAS unsigned*)(lds + (bufoff) + ldsw + _i * 8192), 16, 0, 0); } while (0)
; #define PG8_BAR __builtin_amdgcn_s_barrier()
; template <class Epi, class Sched, bool ALIGN_EPI = false, bool SP2 = false>
; __device__ __forceinline__ void gemm_phase(PG8_LAS unsigned char* lds, const Gemm g, const Sched& S, const Epi& E) {
;     ...
;     for (int i = 0; i < 2; ++i) { int R, C; stage_rc(tid * 16 + i * 8192, R, C); const int Rb = Epi::PERM ? ((R & ~31) + perm32(R & 31)) : R;
;         voffA[i] = (unsigned)(R * K + C) * 2u; voffB[i] = (unsigned)(Rb * K + C) * 2u; }
;     const size_t kstep = (size_t)(BK * 2);
;     const size_t hstep = (size_t)HALF * K * 2;
;     const size_t tstep = 2 * hstep;
;     const unsigned ldsw = (unsigned)wid * 1024u;
;     const int aoff = lds_byte(wr * 64 + fr, fq * 8), boff = lds_byte(wc * 32 + fr, fq * 8);
;     ...
;     Unit cur, nxt; int ui = 0;
;     if (!S.next(0, cur)) return;
;     f32x4 acc[2][2][4][2];
; #pragma unroll
;     for (int a = 0; a < 2; ++a)
; #pragma unroll
;         for (int b = 0; b < 2; ++b)
; #pragma unroll
;             for (int m = 0; m < 4; ++m)
; #pragma unroll
;                 for (int n = 0; n < 2; ++n) acc[a][b][m][n] = (f32x4){0.f, 0.f, 0.f, 0.f};
;     bf16x8 At[4][2], B0[2][2], B1[2][2];
;     const char* cA = (const char*)g.A + (size_t)cur.pm * tstep + (size_t)cur.kt0 * kstep; const char* cB = (const char*)g.Bt + (size_t)cur.pn * tstep + (size_t)cur.kt0 * kstep;
;     S.a_ready(cur);
;     if constexpr (SP2) {
;         PG8_STAGE(PG8_SB(0, 0), cB, voffB); PG8_STAGE(PG8_SB(0, 1), cB + hstep, voffB); PG8_STAGE(PG8_SA(0, 0), cA, voffA); PG8_STAGE(PG8_SA(0, 1), cA + hstep, voffA);
;         if (wr == 1) PG8_BAR;
.LBB0_2641:
	s_waitcnt lgkmcnt(0)
	s_add_u32 s30, s22, 0x2100000
	s_addc_u32 s31, s23, 0
	s_andn2_b64 vcc, exec, s[6:7]
	s_cbranch_vccnz .LBB0_2793
	v_ashrrev_i32_e32 v3, 31, v1
	v_lshrrev_b32_e32 v3, 26, v3
	v_add_u32_e32 v3, v1, v3
	v_ashrrev_i32_e32 v10, 6, v3
	v_bfe_i32 v3, v1, 27, 1
	v_lshlrev_b32_e32 v2, 4, v1
	v_lshrrev_b32_e32 v3, 22, v3
	v_add_u32_e32 v3, v2, v3
	v_and_b32_e32 v3, 0xfffffc00, v3
	v_sub_u32_e32 v3, v2, v3
	v_lshrrev_b32_e32 v4, 4, v3
	v_bitop3_b32 v3, v4, v3, 32 bitop3:0x6c
	v_ashrrev_i32_e32 v5, 31, v3
	v_lshrrev_b32_e32 v5, 26, v5
	v_add_u32_e32 v5, v3, v5
	v_lshlrev_b32_e32 v4, 3, v10
	v_ashrrev_i32_e32 v11, 6, v5
	v_and_b32_e32 v5, 0xc0, v5
	v_and_b32_e32 v4, -16, v4
	v_sub_u32_e32 v3, v3, v5
	v_mov_b32_e32 v5, 1
	v_add_u32_e32 v4, v11, v4
	v_ashrrev_i16_sdwa v3, v5, sext(v3) dst_sel:DWORD dst_unused:UNUSED_PAD src0_sel:DWORD src1_sel:BYTE_0
	v_lshlrev_b32_e32 v6, 5, v10
	v_bfe_i32 v12, v3, 0, 16
	v_lshlrev_b32_e32 v3, 1, v4
	v_lshrrev_b32_e32 v7, 2, v4
	v_and_b32_e32 v8, 3, v11
	s_mov_b32 s1, 0x7ffe0
	v_and_b32_e32 v6, 32, v6
	v_and_b32_e32 v3, 24, v3
	v_and_b32_e32 v7, 4, v7
	v_and_or_b32 v8, v4, s1, v8
	v_or3_b32 v3, v8, v7, v3
	v_add_lshl_u32 v6, v6, v12, 1
	v_add_u32_e32 v2, 0x2000, v2
	v_lshl_add_u32 v186, v3, 13, v6
	v_ashrrev_i32_e32 v3, 31, v2
	v_lshrrev_b32_e32 v3, 22, v3
	v_add_u32_e32 v3, v2, v3
	v_ashrrev_i32_e32 v13, 10, v3
	v_mul_i32_i24_e32 v3, 0x400, v13
	v_sub_u32_e32 v2, v2, v3
	v_lshrrev_b32_e32 v3, 4, v2
	v_bitop3_b32 v2, v3, v2, 32 bitop3:0x6c
	v_lshl_add_u32 v184, v4, 13, v6
	v_ashrrev_i32_e32 v4, 31, v2
	v_lshrrev_b32_e32 v4, 26, v4
	v_add_u32_e32 v4, v2, v4
	v_lshlrev_b32_e32 v3, 3, v13
	v_ashrrev_i32_e32 v14, 6, v4
	v_and_b32_e32 v4, 0xc0, v4
	v_and_b32_e32 v3, -16, v3
	v_sub_u32_e32 v2, v2, v4
	s_add_u32 s57, s22, 0x14100000
	v_add_u32_e32 v3, v14, v3
	v_ashrrev_i16_sdwa v2, v5, sext(v2) dst_sel:DWORD dst_unused:UNUSED_PAD src0_sel:DWORD src1_sel:BYTE_0
	v_and_b32_e32 v5, 3, v14
	s_addc_u32 s60, s23, 0
	v_and_or_b32 v5, v3, s1, v5
	s_ashr_i32 s1, s0, 6
	s_ashr_i32 s19, s18, 31
	s_ashr_i32 s85, s84, 31
	s_ashr_i32 s16, s0, 8
	s_lshl_b32 s61, s1, 10
	s_lshl_b64 s[6:7], s[18:19], 21
	s_lshl_b64 s[8:9], s[84:85], 21
	s_add_u32 s88, s30, s8
	v_lshlrev_b32_e32 v6, 5, v13
	v_bfe_i32 v15, v2, 0, 16
	v_lshlrev_b32_e32 v2, 1, v3
	v_lshrrev_b32_e32 v4, 2, v3
	s_addc_u32 s89, s31, s9
	s_add_i32 s62, s61, 0
	v_and_b32_e32 v6, 32, v6
	v_and_b32_e32 v2, 24, v2
	v_and_b32_e32 v4, 4, v4
	s_add_i32 m0, s62, 0x10000
	v_or3_b32 v2, v5, v4, v2
	v_add_lshl_u32 v4, v6, v15, 1
	global_load_lds_dwordx4 v186, s[88:89]
	s_add_i32 m0, s62, 0x12000
	v_lshl_add_u32 v190, v2, 13, v4
	s_add_u32 s8, s88, 0x100000
	global_load_lds_dwordx4 v190, s[88:89]
	s_addc_u32 s9, s89, 0
	s_add_i32 m0, s62, 0x14000
	v_lshl_add_u32 v188, v3, 13, v4
	global_load_lds_dwordx4 v186, s[8:9]
	s_add_i32 m0, s62, 0x16000
	s_add_u32 s86, s57, s6
	s_addc_u32 s87, s60, s7
	s_add_i32 s63, s62, 0x2000
	global_load_lds_dwordx4 v190, s[8:9]
	s_mov_b32 m0, s62
	s_add_u32 s6, s86, 0x100000
	global_load_lds_dwordx4 v184, s[86:87]
	s_mov_b32 m0, s63
	s_addc_u32 s7, s87, 0
	s_add_i32 s73, s62, 0x4000
	global_load_lds_dwordx4 v188, s[86:87]
	s_mov_b32 m0, s73
	s_add_i32 s75, s62, 0x6000
	global_load_lds_dwordx4 v184, s[6:7]
	s_mov_b32 m0, s75
	v_mov_b32_e32 v193, 0
	global_load_lds_dwordx4 v188, s[6:7]
	s_load_dwordx2 s[36:37], s[34:35], 0x38
	s_load_dwordx4 s[24:27], s[34:35], 0xc0
	v_writelane_b32 v255, s96, 16
	v_mov_b32_e32 v187, v193
	v_mov_b32_e32 v191, v193
	v_mov_b32_e32 v185, v193
	v_mov_b32_e32 v189, v193
	s_cmp_eq_u32 s16, 1
	v_writelane_b32 v255, s97, 17
	s_mov_b32 s94, 0
	v_lshl_add_u64 v[8:9], s[88:89], 0, v[186:187]
	v_lshl_add_u64 v[6:7], s[88:89], 0, v[190:191]
	v_lshl_add_u64 v[4:5], s[86:87], 0, v[184:185]
	v_lshl_add_u64 v[2:3], s[86:87], 0, v[188:189]
	s_cselect_b64 s[38:39], -1, 0
	s_cmp_lg_u32 s16, 1
	s_movk_i32 s97, 0x6000
	s_cbranch_scc1 .LBB0_2644
	s_barrier
	s_setprio 1

; #define PG8_STAGE(bufoff, gbase, voff) do { _Pragma("unroll") for (int _i = 0; _i < 2; ++_i) \
;         __builtin_amdgcn_global_load_lds((const unsigned*)((const char*)(gbase) + (voff)[_i]), (PG8_LAS unsigned*)(lds + (bufoff) + ldsw + _i * 8192), 16, 0, 0); } while (0)
; #define PG8_LDA(dst, b, h) do { _Pragma("unroll") for (int m = 0; m < 4; ++m) _Pragma("unroll") for (int k = 0; k < 2; ++k) dst[m][k] = *(const PG8_LAS bf16x8*)(lds + PG8_SA(b, h) + aoff + m * 2048 + k * 1024); } while (0)
; #define PG8_LDB(dst, b, h) do { _Pragma("unroll") for (int n = 0; n < 2; ++n) _Pragma("unroll") for (int k = 0; k < 2; ++k) dst[n][k] = *(const PG8_LAS bf16x8*)(lds + PG8_SB(b, h) + boff + n * 2048 + k * 1024); } while (0)
; #define PG8_MMA(ai, bj, At, Bt) do { __builtin_amdgcn_s_setprio(1); _Pragma("unroll") for (int m = 0; m < 4; ++m) _Pragma("unroll") for (int n = 0; n < 2; ++n) _Pragma("unroll") for (int k = 0; k < 2; ++k) \
;         acc[ai][bj][m][n] = __builtin_amdgcn_mfma_f32_16x16x32_bf16(Bt[n][k], At[m][k], acc[ai][bj][m][n], 0, 0, 0); __builtin_amdgcn_s_setprio(0); } while (0)
; #define PG8_WAIT_V(n) asm volatile("s_waitcnt vmcnt(" #n ")" ::: "memory")
; #define PG8_WAIT_L(n) asm volatile("s_waitcnt lgkmcnt(" #n ")" ::: "memory")
; #define PG8_BAR __builtin_amdgcn_s_barrier()
; #define PG8_SCHED __builtin_amdgcn_sched_barrier(0)
; template <class Epi, class Sched, bool ALIGN_EPI = false, bool SP2 = false>
; __device__ __forceinline__ void gemm_phase(PG8_LAS unsigned char* lds, const Gemm g, const Sched& S, const Epi& E) {
;     ...
;             PG8_LDB(B0, 0, 0); PG8_LDB(B1, 0, 1); PG8_SCHED; PG8_LDA(At, 0, 0); PG8_STAGE(PG8_SA(1, 1), a1 + hstep, voffA);
;             PG8_WAIT_V(8); PG8_WAIT_L(0); PG8_BAR; PG8_MMA(0, 0, At, B0); PG8_MMA(0, 1, At, B1); PG8_BAR; PG8_SCHED;
;             PG8_LDA(At, 0, 1); PG8_STAGE(PG8_SB(0, 0), b2, voffB); PG8_STAGE(PG8_SB(0, 1), b2 + hstep, voffB); PG8_STAGE(PG8_SA(0, 0), a2, voffA);
;             PG8_WAIT_V(8); PG8_WAIT_L(0); PG8_BAR; PG8_MMA(1, 0, At, B0); PG8_MMA(1, 1, At, B1); PG8_BAR; PG8_SCHED;
.LBB0_2650:
	ds_read_b128 v[10:13], v195
	ds_read_b128 v[14:17], v195 offset:1024
	ds_read_b128 v[42:45], v195 offset:2048
	ds_read_b128 v[46:49], v195 offset:3072
	ds_read_b128 v[50:53], v238
	ds_read_b128 v[54:57], v238 offset:1024
	ds_read_b128 v[58:61], v238 offset:2048
	ds_read_b128 v[62:65], v238 offset:3072
	s_add_u32 s88, s86, 0xfff00080
	s_addc_u32 s89, s87, -1
	s_cmp_eq_u32 s93, 60
	s_cselect_b32 s91, s19, s89
	s_cselect_b32 s90, s69, s88
	s_cselect_b32 s89, s77, s92
	s_cselect_b32 s88, s79, s85
	s_add_i32 m0, s62, 0xc000
	ds_read_b128 v[66:69], v239
	ds_read_b128 v[70:73], v239 offset:1024
	ds_read_b128 v[170:173], v239 offset:2048
	ds_read_b128 v[174:177], v239 offset:3072
	ds_read_b128 v[178:181], v239 offset:4096
	ds_read_b128 v[208:211], v239 offset:5120
	ds_read_b128 v[212:215], v239 offset:6144
	ds_read_b128 v[216:219], v239 offset:7168
	global_load_lds_dwordx4 v200, s[86:87]
	s_add_i32 m0, s62, 0xe000
	s_nop 0
	global_load_lds_dwordx4 v202, s[86:87]
	s_waitcnt vmcnt(8)
	s_waitcnt lgkmcnt(0)
	s_barrier
	s_waitcnt lgkmcnt(0)
	v_mfma_f32_16x16x32_bf16 v[6:9], v[10:13], v[66:69], v[6:9]
	v_mfma_f32_16x16x32_bf16 v[6:9], v[14:17], v[70:73], v[6:9]
	v_mfma_f32_16x16x32_bf16 v[2:5], v[42:45], v[66:69], v[2:5]
	v_mfma_f32_16x16x32_bf16 v[2:5], v[46:49], v[70:73], v[2:5]
	v_mfma_f32_16x16x32_bf16 v[158:161], v[10:13], v[170:173], v[158:161]
	v_mfma_f32_16x16x32_bf16 v[158:161], v[14:17], v[174:177], v[158:161]
	v_mfma_f32_16x16x32_bf16 v[154:157], v[42:45], v[170:173], v[154:157]
	v_mfma_f32_16x16x32_bf16 v[154:157], v[46:49], v[174:177], v[154:157]
	v_mfma_f32_16x16x32_bf16 v[142:145], v[10:13], v[178:181], v[142:145]
	v_mfma_f32_16x16x32_bf16 v[142:145], v[14:17], v[208:211], v[142:145]
	v_mfma_f32_16x16x32_bf16 v[138:141], v[42:45], v[178:181], v[138:141]
	v_mfma_f32_16x16x32_bf16 v[138:141], v[46:49], v[208:211], v[138:141]
	v_mfma_f32_16x16x32_bf16 v[126:129], v[10:13], v[212:215], v[126:129]
	v_mfma_f32_16x16x32_bf16 v[126:129], v[14:17], v[216:219], v[126:129]
	v_mfma_f32_16x16x32_bf16 v[122:125], v[42:45], v[212:215], v[122:125]
	v_mfma_f32_16x16x32_bf16 v[122:125], v[46:49], v[216:219], v[122:125]
	v_mfma_f32_16x16x32_bf16 v[166:169], v[50:53], v[66:69], v[166:169]
	v_mfma_f32_16x16x32_bf16 v[166:169], v[54:57], v[70:73], v[166:169]
	v_mfma_f32_16x16x32_bf16 v[66:69], v[58:61], v[66:69], v[162:165]
	v_mfma_f32_16x16x32_bf16 v[66:69], v[62:65], v[70:73], v[66:69]
	v_mfma_f32_16x16x32_bf16 v[146:149], v[58:61], v[170:173], v[146:149]
	v_mfma_f32_16x16x32_bf16 v[146:149], v[62:65], v[174:177], v[146:149]
	v_mfma_f32_16x16x32_bf16 v[134:137], v[50:53], v[178:181], v[134:137]
	v_mfma_f32_16x16x32_bf16 v[134:137], v[54:57], v[208:211], v[134:137]
	v_mfma_f32_16x16x32_bf16 v[130:133], v[58:61], v[178:181], v[130:133]
	v_mfma_f32_16x16x32_bf16 v[130:133], v[62:65], v[208:211], v[130:133]
	v_mfma_f32_16x16x32_bf16 v[118:121], v[50:53], v[212:215], v[118:121]
	v_mfma_f32_16x16x32_bf16 v[118:121], v[54:57], v[216:219], v[118:121]
	v_mfma_f32_16x16x32_bf16 v[114:117], v[58:61], v[212:215], v[114:117]
	v_mfma_f32_16x16x32_bf16 v[114:117], v[62:65], v[216:219], v[114:117]
	v_mfma_f32_16x16x32_bf16 v[70:73], v[50:53], v[170:173], v[150:153]
	v_mfma_f32_16x16x32_bf16 v[70:73], v[54:57], v[174:177], v[70:73]
	s_barrier
	s_add_i32 vcc_lo, s96, s61
	s_mov_b32 m0, vcc_lo
	ds_read_b128 v[150:153], v239 offset:16384
	ds_read_b128 v[162:165], v239 offset:17408
	ds_read_b128 v[170:173], v239 offset:18432
	ds_read_b128 v[174:177], v239 offset:19456
	ds_read_b128 v[178:181], v239 offset:20480
	ds_read_b128 v[208:211], v239 offset:21504
	ds_read_b128 v[212:215], v239 offset:22528
	ds_read_b128 v[216:219], v239 offset:23552
	global_load_lds_dwordx4 v186, s[88:89]
	s_add_i32 m0, vcc_lo, 0x2000
	s_add_u32 vcc_lo, s88, 0x100000
	s_addc_u32 vcc_hi, s89, 0
	s_add_i32 s58, s70, s61
	global_load_lds_dwordx4 v190, s[88:89]
	s_mov_b32 m0, s58
	s_nop 0
	global_load_lds_dwordx4 v186, vcc
	s_add_i32 m0, s58, 0x2000
	s_nop 0
	global_load_lds_dwordx4 v190, vcc
	s_mov_b32 m0, s62
	s_nop 0
	global_load_lds_dwordx4 v184, s[90:91]
	s_mov_b32 m0, s63
	s_nop 0
	global_load_lds_dwordx4 v188, s[90:91]
	s_waitcnt vmcnt(8)
	s_waitcnt lgkmcnt(0)
	s_barrier
	s_waitcnt lgkmcnt(0)
	v_mfma_f32_16x16x32_bf16 v[110:113], v[10:13], v[150:153], v[110:113]
	v_mfma_f32_16x16x32_bf16 v[110:113], v[14:17], v[162:165], v[110:113]
	v_mfma_f32_16x16x32_bf16 v[106:109], v[42:45], v[150:153], v[106:109]
	v_mfma_f32_16x16x32_bf16 v[106:109], v[46:49], v[162:165], v[106:109]
	v_mfma_f32_16x16x32_bf16 v[94:97], v[10:13], v[170:173], v[94:97]
	v_mfma_f32_16x16x32_bf16 v[94:97], v[14:17], v[174:177], v[94:97]
	v_mfma_f32_16x16x32_bf16 v[90:93], v[42:45], v[170:173], v[90:93]
	v_mfma_f32_16x16x32_bf16 v[90:93], v[46:49], v[174:177], v[90:93]
	v_mfma_f32_16x16x32_bf16 v[78:81], v[10:13], v[178:181], v[78:81]
	v_mfma_f32_16x16x32_bf16 v[78:81], v[14:17], v[208:211], v[78:81]
	v_mfma_f32_16x16x32_bf16 v[74:77], v[42:45], v[178:181], v[74:77]
	v_mfma_f32_16x16x32_bf16 v[74:77], v[46:49], v[208:211], v[74:77]
	v_mfma_f32_16x16x32_bf16 v[10:13], v[10:13], v[212:215], v[30:33]
	v_mfma_f32_16x16x32_bf16 v[10:13], v[14:17], v[216:219], v[10:13]
	v_mfma_f32_16x16x32_bf16 v[14:17], v[42:45], v[212:215], v[26:29]
	v_mfma_f32_16x16x32_bf16 v[14:17], v[46:49], v[216:219], v[14:17]
	v_mfma_f32_16x16x32_bf16 v[26:29], v[50:53], v[150:153], v[102:105]
	v_mfma_f32_16x16x32_bf16 v[42:45], v[54:57], v[162:165], v[26:29]
	v_mfma_f32_16x16x32_bf16 v[26:29], v[58:61], v[150:153], v[98:101]
	v_mfma_f32_16x16x32_bf16 v[46:49], v[62:65], v[162:165], v[26:29]
	v_mfma_f32_16x16x32_bf16 v[26:29], v[50:53], v[170:173], v[86:89]
	v_mfma_f32_16x16x32_bf16 v[86:89], v[54:57], v[174:177], v[26:29]
	v_mfma_f32_16x16x32_bf16 v[26:29], v[58:61], v[170:173], v[82:85]
	v_mfma_f32_16x16x32_bf16 v[82:85], v[62:65], v[174:177], v[26:29]
	v_mfma_f32_16x16x32_bf16 v[26:29], v[50:53], v[178:181], v[38:41]
	v_mfma_f32_16x16x32_bf16 v[38:41], v[54:57], v[208:211], v[26:29]
	v_mfma_f32_16x16x32_bf16 v[26:29], v[58:61], v[178:181], v[34:37]
	v_mfma_f32_16x16x32_bf16 v[34:37], v[62:65], v[208:211], v[26:29]
	v_mfma_f32_16x16x32_bf16 v[22:25], v[50:53], v[212:215], v[22:25]
	v_mfma_f32_16x16x32_bf16 v[22:25], v[54:57], v[216:219], v[22:25]
	v_mfma_f32_16x16x32_bf16 v[18:21], v[58:61], v[212:215], v[18:21]
	v_mfma_f32_16x16x32_bf16 v[18:21], v[62:65], v[216:219], v[18:21]
	s_barrier
; #define PG8_STAGE(bufoff, gbase, voff) do { _Pragma("unroll") for (int _i = 0; _i < 2; ++_i) \
;         __builtin_amdgcn_global_load_lds((const unsigned*)((const char*)(gbase) + (voff)[_i]), (PG8_LAS unsigned*)(lds + (bufoff) + ldsw + _i * 8192), 16, 0, 0); } while (0)
; #define PG8_LDA(dst, b, h) do { _Pragma("unroll") for (int m = 0; m < 4; ++m) _Pragma("unroll") for (int k = 0; k < 2; ++k) dst[m][k] = *(const PG8_LAS bf16x8*)(lds + PG8_SA(b, h) + aoff + m * 2048 + k * 1024); } while (0)
; #define PG8_LDB(dst, b, h) do { _Pragma("unroll") for (int n = 0; n < 2; ++n) _Pragma("unroll") for (int k = 0; k < 2; ++k) dst[n][k] = *(const PG8_LAS bf16x8*)(lds + PG8_SB(b, h) + boff + n * 2048 + k * 1024); } while (0)
; #define PG8_MMA(ai, bj, At, Bt) do { __builtin_amdgcn_s_setprio(1); _Pragma("unroll") for (int m = 0; m < 4; ++m) _Pragma("unroll") for (int n = 0; n < 2; ++n) _Pragma("unroll") for (int k = 0; k < 2; ++k) \
;         acc[ai][bj][m][n] = __builtin_amdgcn_mfma_f32_16x16x32_bf16(Bt[n][k], At[m][k], acc[ai][bj][m][n], 0, 0, 0); __builtin_amdgcn_s_setprio(0); } while (0)
; #define PG8_WAIT_V(n) asm volatile("s_waitcnt vmcnt(" #n ")" ::: "memory")
; #define PG8_WAIT_L(n) asm volatile("s_waitcnt lgkmcnt(" #n ")" ::: "memory")
; #define PG8_BAR __builtin_amdgcn_s_barrier()
; #define PG8_SCHED __builtin_amdgcn_sched_barrier(0)
; template <class Epi, class Sched, bool ALIGN_EPI = false, bool SP2 = false>
; __device__ __forceinline__ void gemm_phase(PG8_LAS unsigned char* lds, const Gemm g, const Sched& S, const Epi& E) {
;     ...
;             PG8_LDB(B0, 1, 0); PG8_LDB(B1, 1, 1); PG8_SCHED; PG8_LDA(At, 1, 0); PG8_STAGE(PG8_SA(0, 1), a2 + hstep, voffA);
;             PG8_WAIT_V(8); PG8_WAIT_L(0); PG8_BAR; PG8_MMA(0, 0, At, B0); PG8_MMA(0, 1, At, B1); PG8_BAR; PG8_SCHED;
;             PG8_LDA(At, 1, 1); PG8_STAGE(PG8_SB(1, 0), b3, voffB); PG8_STAGE(PG8_SB(1, 1), b3 + hstep, voffB); PG8_STAGE(PG8_SA(1, 0), a3, voffA);
;             PG8_WAIT_V(8); PG8_WAIT_L(0); PG8_BAR; PG8_MMA(1, 0, At, B0); PG8_MMA(1, 1, At, B1); PG8_BAR; PG8_SCHED;
	s_add_i32 s58, 0, 0x18000
	s_add_i32 s59, 0, 0x1c000
	v_add_u32_e32 v54, s58, v1
	v_add_u32_e32 v98, s59, v1
	ds_read_b128 v[26:29], v54
	ds_read_b128 v[30:33], v54 offset:1024
	ds_read_b128 v[50:53], v54 offset:2048
	ds_read_b128 v[54:57], v54 offset:3072
	ds_read_b128 v[58:61], v98
	ds_read_b128 v[62:65], v98 offset:1024
	ds_read_b128 v[170:173], v98 offset:2048
	ds_read_b128 v[174:177], v98 offset:3072
	s_add_u32 s90, s90, 0x100000
	s_addc_u32 s91, s91, 0
	s_mov_b32 m0, s73
	ds_read_b128 v[98:101], v239 offset:32768
	ds_read_b128 v[102:105], v239 offset:33792
	ds_read_b128 v[178:181], v239 offset:34816
	ds_read_b128 v[208:211], v239 offset:35840
	ds_read_b128 v[212:215], v239 offset:36864
	ds_read_b128 v[216:219], v239 offset:37888
	ds_read_b128 v[220:223], v239 offset:38912
	ds_read_b128 v[224:227], v239 offset:39936
	global_load_lds_dwordx4 v184, s[90:91]
	s_mov_b32 m0, s75
	s_nop 0
	global_load_lds_dwordx4 v188, s[90:91]
	s_waitcnt vmcnt(8)
	s_waitcnt lgkmcnt(0)
	s_barrier
	s_waitcnt lgkmcnt(0)
	v_mfma_f32_16x16x32_bf16 v[150:153], v[26:29], v[178:181], v[158:161]
	v_mfma_f32_16x16x32_bf16 v[158:161], v[30:33], v[208:211], v[150:153]
	v_mfma_f32_16x16x32_bf16 v[6:9], v[26:29], v[98:101], v[6:9]
	v_mfma_f32_16x16x32_bf16 v[6:9], v[30:33], v[102:105], v[6:9]
	v_mfma_f32_16x16x32_bf16 v[2:5], v[50:53], v[98:101], v[2:5]
	v_mfma_f32_16x16x32_bf16 v[2:5], v[54:57], v[102:105], v[2:5]
	v_mfma_f32_16x16x32_bf16 v[150:153], v[50:53], v[178:181], v[154:157]
	v_mfma_f32_16x16x32_bf16 v[154:157], v[54:57], v[208:211], v[150:153]
	v_mfma_f32_16x16x32_bf16 v[142:145], v[26:29], v[212:215], v[142:145]
	v_mfma_f32_16x16x32_bf16 v[142:145], v[30:33], v[216:219], v[142:145]
	v_mfma_f32_16x16x32_bf16 v[138:141], v[50:53], v[212:215], v[138:141]
	v_mfma_f32_16x16x32_bf16 v[138:141], v[54:57], v[216:219], v[138:141]
	v_mfma_f32_16x16x32_bf16 v[126:129], v[26:29], v[220:223], v[126:129]
	v_mfma_f32_16x16x32_bf16 v[126:129], v[30:33], v[224:227], v[126:129]
	v_mfma_f32_16x16x32_bf16 v[122:125], v[50:53], v[220:223], v[122:125]
	v_mfma_f32_16x16x32_bf16 v[122:125], v[54:57], v[224:227], v[122:125]
	v_mfma_f32_16x16x32_bf16 v[66:69], v[170:173], v[98:101], v[66:69]
	v_mfma_f32_16x16x32_bf16 v[162:165], v[174:177], v[102:105], v[66:69]
	v_mfma_f32_16x16x32_bf16 v[150:153], v[58:61], v[98:101], v[166:169]
	v_mfma_f32_16x16x32_bf16 v[166:169], v[62:65], v[102:105], v[150:153]
	v_mfma_f32_16x16x32_bf16 v[66:69], v[58:61], v[178:181], v[70:73]
	v_mfma_f32_16x16x32_bf16 v[150:153], v[62:65], v[208:211], v[66:69]
	v_mfma_f32_16x16x32_bf16 v[66:69], v[170:173], v[178:181], v[146:149]
	v_mfma_f32_16x16x32_bf16 v[146:149], v[174:177], v[208:211], v[66:69]
	v_mfma_f32_16x16x32_bf16 v[66:69], v[58:61], v[212:215], v[134:137]
	v_mfma_f32_16x16x32_bf16 v[134:137], v[62:65], v[216:219], v[66:69]
	v_mfma_f32_16x16x32_bf16 v[66:69], v[170:173], v[212:215], v[130:133]
	v_mfma_f32_16x16x32_bf16 v[130:133], v[174:177], v[216:219], v[66:69]
	v_mfma_f32_16x16x32_bf16 v[66:69], v[58:61], v[220:223], v[118:121]
	v_mfma_f32_16x16x32_bf16 v[118:121], v[62:65], v[224:227], v[66:69]
	v_mfma_f32_16x16x32_bf16 v[66:69], v[170:173], v[220:223], v[114:117]
	v_mfma_f32_16x16x32_bf16 v[114:117], v[174:177], v[224:227], v[66:69]
	s_barrier
	s_add_i32 s58, s58, s61
	s_add_u32 s100, s88, 0x80
	s_addc_u32 s101, s89, 0
	s_mov_b32 m0, s58
	s_nop 1
	ds_read_b128 v[66:69], v239 offset:49152
	ds_read_b128 v[70:73], v239 offset:50176
	ds_read_b128 v[178:181], v239 offset:51200
	ds_read_b128 v[208:211], v239 offset:52224
	ds_read_b128 v[212:215], v239 offset:53248
	ds_read_b128 v[216:219], v239 offset:54272
	ds_read_b128 v[220:223], v239 offset:55296
	ds_read_b128 v[224:227], v239 offset:56320
	global_load_lds_dwordx4 v186, s[100:101]
	s_add_i32 m0, s58, 0x2000
	s_add_i32 s58, s59, s61
	global_load_lds_dwordx4 v190, s[100:101]
	s_add_u32 s88, s88, 0x100080
	s_addc_u32 s89, s89, 0
	s_add_u32 s100, s90, 0xfff00080
	s_addc_u32 s101, s91, -1
	s_mov_b32 m0, s58
	s_nop 0
	global_load_lds_dwordx4 v186, s[88:89]
	s_add_i32 m0, s58, 0x2000
	s_nop 0
	global_load_lds_dwordx4 v190, s[88:89]
	s_mov_b32 m0, s29
	s_nop 0
	global_load_lds_dwordx4 v184, s[100:101]
	s_mov_b32 m0, s95
	s_nop 0
	global_load_lds_dwordx4 v188, s[100:101]
	s_waitcnt vmcnt(8)
	s_waitcnt lgkmcnt(0)
	s_barrier
	s_waitcnt lgkmcnt(0)
	v_mfma_f32_16x16x32_bf16 v[98:101], v[26:29], v[66:69], v[110:113]
	v_mfma_f32_16x16x32_bf16 v[110:113], v[30:33], v[70:73], v[98:101]
	v_mfma_f32_16x16x32_bf16 v[94:97], v[26:29], v[178:181], v[94:97]
	v_mfma_f32_16x16x32_bf16 v[94:97], v[30:33], v[208:211], v[94:97]
	v_mfma_f32_16x16x32_bf16 v[78:81], v[26:29], v[212:215], v[78:81]
	v_mfma_f32_16x16x32_bf16 v[78:81], v[30:33], v[216:219], v[78:81]
	v_mfma_f32_16x16x32_bf16 v[10:13], v[26:29], v[220:223], v[10:13]
	v_mfma_f32_16x16x32_bf16 v[30:33], v[30:33], v[224:227], v[10:13]
	v_mfma_f32_16x16x32_bf16 v[98:101], v[50:53], v[66:69], v[106:109]
	v_mfma_f32_16x16x32_bf16 v[106:109], v[54:57], v[70:73], v[98:101]
	v_mfma_f32_16x16x32_bf16 v[90:93], v[50:53], v[178:181], v[90:93]
	v_mfma_f32_16x16x32_bf16 v[90:93], v[54:57], v[208:211], v[90:93]
	v_mfma_f32_16x16x32_bf16 v[74:77], v[50:53], v[212:215], v[74:77]
	v_mfma_f32_16x16x32_bf16 v[74:77], v[54:57], v[216:219], v[74:77]
	v_mfma_f32_16x16x32_bf16 v[10:13], v[50:53], v[220:223], v[14:17]
	v_mfma_f32_16x16x32_bf16 v[26:29], v[54:57], v[224:227], v[10:13]
	v_mfma_f32_16x16x32_bf16 v[10:13], v[58:61], v[66:69], v[42:45]
	v_mfma_f32_16x16x32_bf16 v[102:105], v[62:65], v[70:73], v[10:13]
	v_mfma_f32_16x16x32_bf16 v[10:13], v[170:173], v[66:69], v[46:49]
	v_mfma_f32_16x16x32_bf16 v[98:101], v[174:177], v[70:73], v[10:13]
	v_mfma_f32_16x16x32_bf16 v[10:13], v[58:61], v[178:181], v[86:89]
	v_mfma_f32_16x16x32_bf16 v[86:89], v[62:65], v[208:211], v[10:13]
	v_mfma_f32_16x16x32_bf16 v[10:13], v[170:173], v[178:181], v[82:85]
	v_mfma_f32_16x16x32_bf16 v[82:85], v[174:177], v[208:211], v[10:13]
	v_mfma_f32_16x16x32_bf16 v[10:13], v[58:61], v[212:215], v[38:41]
	v_mfma_f32_16x16x32_bf16 v[38:41], v[62:65], v[216:219], v[10:13]
	v_mfma_f32_16x16x32_bf16 v[10:13], v[170:173], v[212:215], v[34:37]
	v_mfma_f32_16x16x32_bf16 v[34:37], v[174:177], v[216:219], v[10:13]
	v_mfma_f32_16x16x32_bf16 v[10:13], v[58:61], v[220:223], v[22:25]
	v_mfma_f32_16x16x32_bf16 v[22:25], v[62:65], v[224:227], v[10:13]
	v_mfma_f32_16x16x32_bf16 v[10:13], v[170:173], v[220:223], v[18:21]
	v_mfma_f32_16x16x32_bf16 v[18:21], v[174:177], v[224:227], v[10:13]
	s_barrier
	s_add_i32 s93, s93, 2
	s_add_u32 s86, s86, 0x100
	s_addc_u32 s87, s87, 0
	s_add_u32 s85, s85, 0x100
	s_addc_u32 s92, s92, 0
	s_cmp_gt_u32 s93, 61
	s_cbranch_scc0 .LBB0_2650
	s_and_b64 vcc, exec, s[42:43]
	s_cbranch_vccz .LBB0_2653
	s_barrier

; #define PG8_WAIT_V(n) asm volatile("s_waitcnt vmcnt(" #n ")" ::: "memory")
; #define PG8_BAR __builtin_amdgcn_s_barrier()
; template <class Epi, class Sched, bool ALIGN_EPI = false, bool SP2 = false>
; __device__ __forceinline__ void gemm_phase(PG8_LAS unsigned char* lds, const Gemm g, const Sched& S, const Epi& E) {
;     ...
;     PG8_WAIT_V(0);
;     if constexpr (!ALIGN_EPI) { if (wr == 0) PG8_BAR; }
;     PG8_BAR;
; __device__ __forceinline__ void xcd_barrier(const XcdBarrier& b) {
;     asm volatile("s_waitcnt vmcnt(0)" ::: "memory");
;     __syncthreads();
;     if (threadIdx.x == 0) {
;         unsigned* bar = b.bar;
;         __builtin_amdgcn_s_waitcnt(0);
;         unsigned nloc = b.st[0], nx = b.st[1];
;         if (nloc == 0u) { xcd_barrier_complete(bar, b.x, nloc, nx); b.st[0] = nloc; b.st[1] = nx; }
.LBB0_3083:
	s_waitcnt vmcnt(0)
	v_readlane_b32 s6, v255, 7
	v_readlane_b32 s7, v255, 8
	s_setprio 0
	s_barrier
	s_and_saveexec_b64 s[0:1], s[6:7]
	s_xor_b64 s[6:7], exec, s[0:1]
	s_cbranch_execz .LBB0_3136
	s_add_i32 s0, 0, 0x24020
	v_mov_b32_e32 v1, s0
	s_waitcnt vmcnt(0) expcnt(0) lgkmcnt(0)
	ds_read_b32 v3, v1
	s_add_i32 s0, 0, 0x24024
	v_mov_b32_e32 v1, s0
	ds_read_b32 v1, v1
	s_waitcnt lgkmcnt(1)
	v_cmp_ne_u32_e32 vcc, 0, v3
	s_cbranch_vccnz .LBB0_3099
	v_readlane_b32 s8, v255, 2
	v_readlane_b32 s9, v255, 3
	v_readlane_b32 s28, v255, 0
	s_load_dwordx2 s[0:1], s[8:9], 0x4
	v_readlane_b32 s29, v255, 1
	s_add_u32 s8, s28, 0x4200
	s_addc_u32 s9, s29, 0
	s_add_u32 s10, s28, 0x4400
	s_addc_u32 s11, s29, 0
	s_add_u32 s12, s28, 0x4500
	s_addc_u32 s13, s29, 0
	s_add_u32 s14, s28, 0x4600
	s_addc_u32 s15, s29, 0
	s_add_u32 s16, s28, 0x4700
	s_addc_u32 s17, s29, 0
	s_add_u32 s18, s28, 0x4800
	s_addc_u32 s19, s29, 0
	s_add_u32 s20, s28, 0x4900
	s_addc_u32 s21, s29, 0
	s_add_u32 s22, s28, 0x4a00
	s_addc_u32 s23, s29, 0
	s_add_u32 s24, s28, 0x4b00
	s_addc_u32 s25, s29, 0
	s_add_u32 s26, s28, 0x4c00
	s_addc_u32 s27, s29, 0
	s_add_u32 s30, s28, 0x4d00
	s_addc_u32 s31, s29, 0
	s_add_u32 s34, s28, 0x4e00
	s_addc_u32 s35, s29, 0
	s_add_u32 s36, s28, 0x4f00
	s_addc_u32 s37, s29, 0
	s_add_u32 s38, s28, 0x5000
	s_addc_u32 s39, s29, 0
	s_add_u32 s40, s28, 0x5100
	s_addc_u32 s41, s29, 0
	s_add_u32 s42, s28, 0x5200
	s_addc_u32 s43, s29, 0
	s_waitcnt lgkmcnt(0)
	s_mul_i32 s0, s0, s33
	s_add_u32 s44, s28, 0x5300
	s_mul_i32 s0, s0, s1
	s_addc_u32 s45, s29, 0
	s_mov_b32 s1, 1
	v_mov_b32_e32 v17, 0
	s_branch .LBB0_3087

; #define PG8_STAGE(bufoff, gbase, voff) do { _Pragma("unroll") for (int _i = 0; _i < 2; ++_i) \
;         __builtin_amdgcn_global_load_lds((const unsigned*)((const char*)(gbase) + (voff)[_i]), (PG8_LAS unsigned*)(lds + (bufoff) + ldsw + _i * 8192), 16, 0, 0); } while (0)
; #define PG8_BAR __builtin_amdgcn_s_barrier()
; template <class Epi, class Sched, bool ALIGN_EPI = false, bool SP2 = false>
; __device__ __forceinline__ void gemm_phase(PG8_LAS unsigned char* lds, const Gemm g, const Sched& S, const Epi& E) {
;     ...
;     for (int i = 0; i < 2; ++i) { int R, C; stage_rc(tid * 16 + i * 8192, R, C); const int Rb = Epi::PERM ? ((R & ~31) + perm32(R & 31)) : R;
;         voffA[i] = (unsigned)(R * K + C) * 2u; voffB[i] = (unsigned)(Rb * K + C) * 2u; }
;     const size_t kstep = (size_t)(BK * 2);
;     const size_t hstep = (size_t)HALF * K * 2;
;     const size_t tstep = 2 * hstep;
;     const unsigned ldsw = (unsigned)wid * 1024u;
;     const int aoff = lds_byte(wr * 64 + fr, fq * 8), boff = lds_byte(wc * 32 + fr, fq * 8);
;     ...
;     Unit cur, nxt; int ui = 0;
;     if (!S.next(0, cur)) return;
;     f32x4 acc[2][2][4][2];
; #pragma unroll
;     for (int a = 0; a < 2; ++a)
; #pragma unroll
;         for (int b = 0; b < 2; ++b)
; #pragma unroll
;             for (int m = 0; m < 4; ++m)
; #pragma unroll
;                 for (int n = 0; n < 2; ++n) acc[a][b][m][n] = (f32x4){0.f, 0.f, 0.f, 0.f};
;     bf16x8 At[4][2], B0[2][2], B1[2][2];
;     const char* cA = (const char*)g.A + (size_t)cur.pm * tstep + (size_t)cur.kt0 * kstep; const char* cB = (const char*)g.Bt + (size_t)cur.pn * tstep + (size_t)cur.kt0 * kstep;
;     S.a_ready(cur);
;     if constexpr (SP2) {
;         PG8_STAGE(PG8_SB(0, 0), cB, voffB); PG8_STAGE(PG8_SB(0, 1), cB + hstep, voffB); PG8_STAGE(PG8_SA(0, 0), cA, voffA); PG8_STAGE(PG8_SA(0, 1), cA + hstep, voffA);
;         if (wr == 1) PG8_BAR;
.LBB0_3498:
	s_andn2_b64 vcc, exec, s[8:9]
	s_cbranch_vccnz .LBB0_3552
	s_waitcnt vmcnt(9)
	v_ashrrev_i32_e32 v3, 31, v1
	v_lshrrev_b32_e32 v3, 26, v3
	v_add_u32_e32 v3, v1, v3
	s_waitcnt vmcnt(4)
	v_ashrrev_i32_e32 v10, 6, v3
	v_bfe_i32 v3, v1, 27, 1
	v_lshlrev_b32_e32 v2, 4, v1
	v_lshrrev_b32_e32 v3, 22, v3
	v_add_u32_e32 v3, v2, v3
	v_and_b32_e32 v3, 0xfffffc00, v3
	v_sub_u32_e32 v3, v2, v3
	v_lshrrev_b32_e32 v4, 4, v3
	v_bitop3_b32 v3, v4, v3, 32 bitop3:0x6c
	v_ashrrev_i32_e32 v5, 31, v3
	v_lshrrev_b32_e32 v5, 26, v5
	v_add_u32_e32 v5, v3, v5
	v_lshlrev_b32_e32 v4, 3, v10
	v_ashrrev_i32_e32 v12, 6, v5
	v_and_b32_e32 v5, 0xc0, v5
	v_and_b32_e32 v4, 0xffff0, v4
	v_sub_u32_e32 v3, v3, v5
	v_mov_b32_e32 v5, 1
	s_load_dwordx4 s[8:11], s[6:7], 0xe0
	v_add_u32_e32 v4, v12, v4
	v_lshlrev_b32_e32 v6, 5, v10
	v_ashrrev_i16_sdwa v3, v5, sext(v3) dst_sel:DWORD dst_unused:UNUSED_PAD src0_sel:DWORD src1_sel:BYTE_0
	s_movk_i32 s6, 0x3000
	v_and_b32_e32 v11, 32, v6
	v_bfe_i32 v13, v3, 0, 16
	v_mul_lo_u32 v3, v4, s6
	v_or_b32_e32 v3, v3, v11
	v_add_u32_e32 v2, 0x2000, v2
	v_add_lshl_u32 v130, v3, v13, 1
	v_ashrrev_i32_e32 v3, 31, v2
	v_lshrrev_b32_e32 v3, 22, v3
	v_add_u32_e32 v3, v2, v3
	s_waitcnt lgkmcnt(0)
	s_add_u32 s46, s10, 0x2cd00000
	s_waitcnt vmcnt(2)
	v_ashrrev_i32_e32 v14, 10, v3
	s_addc_u32 s47, s11, 0
	v_mul_i32_i24_e32 v3, 0x400, v14
	s_add_u32 s48, s10, 0xe100000
	v_sub_u32_e32 v2, v2, v3
	s_addc_u32 s49, s11, 0
	v_lshrrev_b32_e32 v3, 4, v2
	s_ashr_i32 s18, s20, 6
	s_ashr_i32 s15, s14, 31
	s_ashr_i32 s7, s20, 8
	v_bitop3_b32 v2, v3, v2, 32 bitop3:0x6c
	s_lshl_b32 s50, s18, 10
	s_lshl_b64 s[16:17], s[14:15], 7
	s_mul_i32 s22, s5, 0x600000
	v_ashrrev_i32_e32 v4, 31, v2
	s_mul_hi_i32 s15, s5, 0x600000
	s_add_u32 s22, s48, s22
	v_lshrrev_b32_e32 v4, 26, v4
	s_addc_u32 s15, s49, s15
	v_add_u32_e32 v4, v2, v4
	s_add_u32 s40, s22, s16
	v_lshlrev_b32_e32 v3, 3, v14
	v_ashrrev_i32_e32 v15, 6, v4
	v_and_b32_e32 v4, 0xc0, v4
	s_addc_u32 s41, s15, s17
	s_add_i32 s51, s50, 0
	v_and_b32_e32 v3, 0xffff0, v3
	v_sub_u32_e32 v2, v2, v4
	s_add_i32 m0, s51, 0x10000
	v_add_u32_e32 v3, v15, v3
	v_lshlrev_b32_e32 v6, 5, v14
	v_ashrrev_i16_sdwa v2, v5, sext(v2) dst_sel:DWORD dst_unused:UNUSED_PAD src0_sel:DWORD src1_sel:BYTE_0
	s_mul_i32 s21, s4, 0x600000
	global_load_lds_dwordx4 v130, s[40:41]
	s_add_i32 m0, s51, 0x12000
	v_and_b32_e32 v16, 32, v6
	v_bfe_i32 v17, v2, 0, 16
	v_mul_lo_u32 v2, v3, s6
	s_mul_hi_i32 s19, s4, 0x600000
	s_add_u32 s15, s46, s21
	v_or_b32_e32 v2, v2, v16
	s_addc_u32 s19, s47, s19
	v_add_lshl_u32 v132, v2, v17, 1
	s_add_u32 s22, s40, 0x300000
	global_load_lds_dwordx4 v132, s[40:41]
	s_addc_u32 s23, s41, 0
	s_add_i32 m0, s51, 0x14000
	v_mov_b32_e32 v135, 0
	global_load_lds_dwordx4 v130, s[22:23]
	s_add_i32 m0, s51, 0x16000
	s_add_u32 s38, s15, s16
	s_addc_u32 s39, s19, s17
	s_add_i32 s52, s51, 0x2000
	global_load_lds_dwordx4 v132, s[22:23]
	s_mov_b32 m0, s51
	s_add_u32 s16, s38, 0x300000
	global_load_lds_dwordx4 v130, s[38:39]
	s_mov_b32 m0, s52
	s_addc_u32 s17, s39, 0
	s_add_i32 s53, s51, 0x4000
	global_load_lds_dwordx4 v132, s[38:39]
	s_mov_b32 m0, s53
	s_add_i32 s54, s51, 0x6000
	global_load_lds_dwordx4 v130, s[16:17]
	s_mov_b32 m0, s54
	v_mov_b32_e32 v131, v135
	global_load_lds_dwordx4 v132, s[16:17]
	v_mov_b32_e32 v133, v135
	s_cmp_eq_u32 s7, 1
	s_mov_b32 s15, 0
	v_lshl_add_u64 v[8:9], s[40:41], 0, v[130:131]
	v_lshl_add_u64 v[6:7], s[40:41], 0, v[132:133]
	v_lshl_add_u64 v[4:5], s[38:39], 0, v[130:131]
	v_lshl_add_u64 v[2:3], s[38:39], 0, v[132:133]
	s_cselect_b64 s[16:17], -1, 0
	s_cmp_lg_u32 s7, 1
	s_movk_i32 s55, 0x4000
	s_cbranch_scc1 .LBB0_3501
	s_barrier
	s_setprio 1

; #define PG8_STAGE(bufoff, gbase, voff) do { _Pragma("unroll") for (int _i = 0; _i < 2; ++_i) \
;         __builtin_amdgcn_global_load_lds((const unsigned*)((const char*)(gbase) + (voff)[_i]), (PG8_LAS unsigned*)(lds + (bufoff) + ldsw + _i * 8192), 16, 0, 0); } while (0)
; #define PG8_LDA(dst, b, h) do { _Pragma("unroll") for (int m = 0; m < 4; ++m) _Pragma("unroll") for (int k = 0; k < 2; ++k) dst[m][k] = *(const PG8_LAS bf16x8*)(lds + PG8_SA(b, h) + aoff + m * 2048 + k * 1024); } while (0)
; #define PG8_LDB(dst, b, h) do { _Pragma("unroll") for (int n = 0; n < 2; ++n) _Pragma("unroll") for (int k = 0; k < 2; ++k) dst[n][k] = *(const PG8_LAS bf16x8*)(lds + PG8_SB(b, h) + boff + n * 2048 + k * 1024); } while (0)
; #define PG8_MMA(ai, bj, At, Bt) do { __builtin_amdgcn_s_setprio(1); _Pragma("unroll") for (int m = 0; m < 4; ++m) _Pragma("unroll") for (int n = 0; n < 2; ++n) _Pragma("unroll") for (int k = 0; k < 2; ++k) \
;         acc[ai][bj][m][n] = __builtin_amdgcn_mfma_f32_16x16x32_bf16(Bt[n][k], At[m][k], acc[ai][bj][m][n], 0, 0, 0); __builtin_amdgcn_s_setprio(0); } while (0)
; #define PG8_WAIT_V(n) asm volatile("s_waitcnt vmcnt(" #n ")" ::: "memory")
; #define PG8_WAIT_L(n) asm volatile("s_waitcnt lgkmcnt(" #n ")" ::: "memory")
; #define PG8_BAR __builtin_amdgcn_s_barrier()
; #define PG8_SCHED __builtin_amdgcn_sched_barrier(0)
; template <class Epi, class Sched, bool ALIGN_EPI = false, bool SP2 = false>
; __device__ __forceinline__ void gemm_phase(PG8_LAS unsigned char* lds, const Gemm g, const Sched& S, const Epi& E) {
;     ...
;             PG8_LDB(B0, 0, 0); PG8_LDB(B1, 0, 1); PG8_SCHED; PG8_LDA(At, 0, 0); PG8_STAGE(PG8_SA(1, 1), a1 + hstep, voffA);
;             PG8_WAIT_V(8); PG8_WAIT_L(0); PG8_BAR; PG8_MMA(0, 0, At, B0); PG8_MMA(0, 1, At, B1); PG8_BAR; PG8_SCHED;
;             PG8_LDA(At, 0, 1); PG8_STAGE(PG8_SB(0, 0), b2, voffB); PG8_STAGE(PG8_SB(0, 1), b2 + hstep, voffB); PG8_STAGE(PG8_SA(0, 0), a2, voffA);
;             PG8_WAIT_V(8); PG8_WAIT_L(0); PG8_BAR; PG8_MMA(1, 0, At, B0); PG8_MMA(1, 1, At, B1); PG8_BAR; PG8_SCHED;
.LBB0_3522:
	ds_read_b128 v[144:147], v177
	ds_read_b128 v[148:151], v177 offset:1024
	ds_read_b128 v[152:155], v177 offset:2048
	ds_read_b128 v[156:159], v177 offset:3072
	ds_read_b128 v[160:163], v178
	ds_read_b128 v[164:167], v178 offset:1024
	ds_read_b128 v[168:171], v178 offset:2048
	ds_read_b128 v[172:175], v178 offset:3072
	s_add_u32 s40, s38, 0x100
	s_addc_u32 s41, s39, 0
	s_cmp_eq_u32 s69, s71
	s_cselect_b32 s45, s35, s41
	s_cselect_b32 s44, s34, s40
	s_cselect_b32 s43, s37, s70
	s_cselect_b32 s42, s36, s31
	s_add_i32 m0, s51, 0xc000
	ds_read_b128 v[180:183], v179
	ds_read_b128 v[184:187], v179 offset:1024
	ds_read_b128 v[188:191], v179 offset:2048
	ds_read_b128 v[192:195], v179 offset:3072
	ds_read_b128 v[196:199], v179 offset:4096
	ds_read_b128 v[200:203], v179 offset:5120
	ds_read_b128 v[204:207], v179 offset:6144
	ds_read_b128 v[208:211], v179 offset:7168
	global_load_lds_dwordx4 v138, s[38:39]
	s_add_i32 m0, s51, 0xe000
	s_nop 0
	global_load_lds_dwordx4 v140, s[38:39]
	s_waitcnt vmcnt(8)
	s_waitcnt lgkmcnt(0)
	s_barrier
	s_waitcnt lgkmcnt(0)
	v_mfma_f32_16x16x32_bf16 v[126:129], v[144:147], v[180:183], v[126:129]
	v_mfma_f32_16x16x32_bf16 v[126:129], v[148:151], v[184:187], v[126:129]
	v_mfma_f32_16x16x32_bf16 v[122:125], v[152:155], v[180:183], v[122:125]
	v_mfma_f32_16x16x32_bf16 v[122:125], v[156:159], v[184:187], v[122:125]
	v_mfma_f32_16x16x32_bf16 v[110:113], v[144:147], v[188:191], v[110:113]
	v_mfma_f32_16x16x32_bf16 v[110:113], v[148:151], v[192:195], v[110:113]
	v_mfma_f32_16x16x32_bf16 v[106:109], v[152:155], v[188:191], v[106:109]
	v_mfma_f32_16x16x32_bf16 v[106:109], v[156:159], v[192:195], v[106:109]
	v_mfma_f32_16x16x32_bf16 v[94:97], v[144:147], v[196:199], v[94:97]
	v_mfma_f32_16x16x32_bf16 v[94:97], v[148:151], v[200:203], v[94:97]
	v_mfma_f32_16x16x32_bf16 v[90:93], v[152:155], v[196:199], v[90:93]
	v_mfma_f32_16x16x32_bf16 v[90:93], v[156:159], v[200:203], v[90:93]
	v_mfma_f32_16x16x32_bf16 v[78:81], v[144:147], v[204:207], v[78:81]
	v_mfma_f32_16x16x32_bf16 v[78:81], v[148:151], v[208:211], v[78:81]
	v_mfma_f32_16x16x32_bf16 v[74:77], v[152:155], v[204:207], v[74:77]
	v_mfma_f32_16x16x32_bf16 v[74:77], v[156:159], v[208:211], v[74:77]
	v_mfma_f32_16x16x32_bf16 v[118:121], v[160:163], v[180:183], v[118:121]
	v_mfma_f32_16x16x32_bf16 v[118:121], v[164:167], v[184:187], v[118:121]
	v_mfma_f32_16x16x32_bf16 v[114:117], v[168:171], v[180:183], v[114:117]
	v_mfma_f32_16x16x32_bf16 v[114:117], v[172:175], v[184:187], v[114:117]
	v_mfma_f32_16x16x32_bf16 v[102:105], v[160:163], v[188:191], v[102:105]
	v_mfma_f32_16x16x32_bf16 v[102:105], v[164:167], v[192:195], v[102:105]
	v_mfma_f32_16x16x32_bf16 v[98:101], v[168:171], v[188:191], v[98:101]
	v_mfma_f32_16x16x32_bf16 v[98:101], v[172:175], v[192:195], v[98:101]
	v_mfma_f32_16x16x32_bf16 v[86:89], v[160:163], v[196:199], v[86:89]
	v_mfma_f32_16x16x32_bf16 v[86:89], v[164:167], v[200:203], v[86:89]
	v_mfma_f32_16x16x32_bf16 v[82:85], v[168:171], v[196:199], v[82:85]
	v_mfma_f32_16x16x32_bf16 v[82:85], v[172:175], v[200:203], v[82:85]
	v_mfma_f32_16x16x32_bf16 v[70:73], v[160:163], v[204:207], v[70:73]
	v_mfma_f32_16x16x32_bf16 v[70:73], v[164:167], v[208:211], v[70:73]
	v_mfma_f32_16x16x32_bf16 v[66:69], v[168:171], v[204:207], v[66:69]
	v_mfma_f32_16x16x32_bf16 v[66:69], v[172:175], v[208:211], v[66:69]
	s_barrier
	s_add_i32 s38, s63, s50
	s_mov_b32 m0, s38
	ds_read_b128 v[180:183], v179 offset:16384
	ds_read_b128 v[184:187], v179 offset:17408
	ds_read_b128 v[188:191], v179 offset:18432
	ds_read_b128 v[192:195], v179 offset:19456
	ds_read_b128 v[196:199], v179 offset:20480
	ds_read_b128 v[200:203], v179 offset:21504
	ds_read_b128 v[204:207], v179 offset:22528
	ds_read_b128 v[208:211], v179 offset:23552
	global_load_lds_dwordx4 v130, s[42:43]
	s_add_i32 m0, s38, 0x2000
	s_add_u32 s38, s42, 0x300000
	s_addc_u32 s39, s43, 0
	s_add_i32 s58, s64, s50
	global_load_lds_dwordx4 v132, s[42:43]
	s_mov_b32 m0, s58
	s_nop 0
	global_load_lds_dwordx4 v130, s[38:39]
	s_add_i32 m0, s58, 0x2000
	s_nop 0
	global_load_lds_dwordx4 v132, s[38:39]
	s_mov_b32 m0, s51
	s_nop 0
	global_load_lds_dwordx4 v130, s[44:45]
	s_mov_b32 m0, s52
	s_nop 0
	global_load_lds_dwordx4 v132, s[44:45]
	s_waitcnt vmcnt(8)
	s_waitcnt lgkmcnt(0)
	s_barrier
	s_waitcnt lgkmcnt(0)
	v_mfma_f32_16x16x32_bf16 v[62:65], v[144:147], v[180:183], v[62:65]
	v_mfma_f32_16x16x32_bf16 v[62:65], v[148:151], v[184:187], v[62:65]
	v_mfma_f32_16x16x32_bf16 v[58:61], v[152:155], v[180:183], v[58:61]
	v_mfma_f32_16x16x32_bf16 v[58:61], v[156:159], v[184:187], v[58:61]
	v_mfma_f32_16x16x32_bf16 v[46:49], v[144:147], v[188:191], v[46:49]
	v_mfma_f32_16x16x32_bf16 v[46:49], v[148:151], v[192:195], v[46:49]
	v_mfma_f32_16x16x32_bf16 v[42:45], v[152:155], v[188:191], v[42:45]
	v_mfma_f32_16x16x32_bf16 v[42:45], v[156:159], v[192:195], v[42:45]
	v_mfma_f32_16x16x32_bf16 v[30:33], v[144:147], v[196:199], v[30:33]
	v_mfma_f32_16x16x32_bf16 v[30:33], v[148:151], v[200:203], v[30:33]
	v_mfma_f32_16x16x32_bf16 v[26:29], v[152:155], v[196:199], v[26:29]
	v_mfma_f32_16x16x32_bf16 v[26:29], v[156:159], v[200:203], v[26:29]
	v_mfma_f32_16x16x32_bf16 v[14:17], v[144:147], v[204:207], v[14:17]
	v_mfma_f32_16x16x32_bf16 v[14:17], v[148:151], v[208:211], v[14:17]
	v_mfma_f32_16x16x32_bf16 v[10:13], v[152:155], v[204:207], v[10:13]
	v_mfma_f32_16x16x32_bf16 v[10:13], v[156:159], v[208:211], v[10:13]
	v_mfma_f32_16x16x32_bf16 v[54:57], v[160:163], v[180:183], v[54:57]
	v_mfma_f32_16x16x32_bf16 v[54:57], v[164:167], v[184:187], v[54:57]
	v_mfma_f32_16x16x32_bf16 v[50:53], v[168:171], v[180:183], v[50:53]
	v_mfma_f32_16x16x32_bf16 v[50:53], v[172:175], v[184:187], v[50:53]
	v_mfma_f32_16x16x32_bf16 v[38:41], v[160:163], v[188:191], v[38:41]
	v_mfma_f32_16x16x32_bf16 v[38:41], v[164:167], v[192:195], v[38:41]
	v_mfma_f32_16x16x32_bf16 v[34:37], v[168:171], v[188:191], v[34:37]
	v_mfma_f32_16x16x32_bf16 v[34:37], v[172:175], v[192:195], v[34:37]
	v_mfma_f32_16x16x32_bf16 v[22:25], v[160:163], v[196:199], v[22:25]
	v_mfma_f32_16x16x32_bf16 v[22:25], v[164:167], v[200:203], v[22:25]
	v_mfma_f32_16x16x32_bf16 v[18:21], v[168:171], v[196:199], v[18:21]
	v_mfma_f32_16x16x32_bf16 v[18:21], v[172:175], v[200:203], v[18:21]
	v_mfma_f32_16x16x32_bf16 v[6:9], v[160:163], v[204:207], v[6:9]
	v_mfma_f32_16x16x32_bf16 v[6:9], v[164:167], v[208:211], v[6:9]
	v_mfma_f32_16x16x32_bf16 v[2:5], v[168:171], v[204:207], v[2:5]
	v_mfma_f32_16x16x32_bf16 v[2:5], v[172:175], v[208:211], v[2:5]
	s_barrier
; #define PG8_STAGE(bufoff, gbase, voff) do { _Pragma("unroll") for (int _i = 0; _i < 2; ++_i) \
;         __builtin_amdgcn_global_load_lds((const unsigned*)((const char*)(gbase) + (voff)[_i]), (PG8_LAS unsigned*)(lds + (bufoff) + ldsw + _i * 8192), 16, 0, 0); } while (0)
; #define PG8_LDA(dst, b, h) do { _Pragma("unroll") for (int m = 0; m < 4; ++m) _Pragma("unroll") for (int k = 0; k < 2; ++k) dst[m][k] = *(const PG8_LAS bf16x8*)(lds + PG8_SA(b, h) + aoff + m * 2048 + k * 1024); } while (0)
; #define PG8_LDB(dst, b, h) do { _Pragma("unroll") for (int n = 0; n < 2; ++n) _Pragma("unroll") for (int k = 0; k < 2; ++k) dst[n][k] = *(const PG8_LAS bf16x8*)(lds + PG8_SB(b, h) + boff + n * 2048 + k * 1024); } while (0)
; #define PG8_MMA(ai, bj, At, Bt) do { __builtin_amdgcn_s_setprio(1); _Pragma("unroll") for (int m = 0; m < 4; ++m) _Pragma("unroll") for (int n = 0; n < 2; ++n) _Pragma("unroll") for (int k = 0; k < 2; ++k) \
;         acc[ai][bj][m][n] = __builtin_amdgcn_mfma_f32_16x16x32_bf16(Bt[n][k], At[m][k], acc[ai][bj][m][n], 0, 0, 0); __builtin_amdgcn_s_setprio(0); } while (0)
; #define PG8_WAIT_V(n) asm volatile("s_waitcnt vmcnt(" #n ")" ::: "memory")
; #define PG8_WAIT_L(n) asm volatile("s_waitcnt lgkmcnt(" #n ")" ::: "memory")
; #define PG8_BAR __builtin_amdgcn_s_barrier()
; #define PG8_SCHED __builtin_amdgcn_sched_barrier(0)
;     __device__ __forceinline__ void operator()(const f32x4 (&acc)[2][2][4][2], const Unit& u, int wr, int wc, int fr, int fq) const {
;     ...
;         if (u.ntu != 192) {
; template <class Epi, class Sched, bool ALIGN_EPI = false, bool SP2 = false>
; __device__ __forceinline__ void gemm_phase(PG8_LAS unsigned char* lds, const Gemm g, const Sched& S, const Epi& E) {
;     ...
;             PG8_LDB(B0, 1, 0); PG8_LDB(B1, 1, 1); PG8_SCHED; PG8_LDA(At, 1, 0); PG8_STAGE(PG8_SA(0, 1), a2 + hstep, voffA);
;             PG8_WAIT_V(8); PG8_WAIT_L(0); PG8_BAR; PG8_MMA(0, 0, At, B0); PG8_MMA(0, 1, At, B1); PG8_BAR; PG8_SCHED;
;             PG8_LDA(At, 1, 1); PG8_STAGE(PG8_SB(1, 0), b3, voffB); PG8_STAGE(PG8_SB(1, 1), b3 + hstep, voffB); PG8_STAGE(PG8_SA(1, 0), a3, voffA);
;             PG8_WAIT_V(8); PG8_WAIT_L(0); PG8_BAR; PG8_MMA(1, 0, At, B0); PG8_MMA(1, 1, At, B1); PG8_BAR; PG8_SCHED;
	s_add_i32 s58, 0, 0x18000
	v_add_u32_e32 v134, s58, v1
	s_add_i32 s59, 0, 0x1c000
	ds_read_b128 v[144:147], v134
	ds_read_b128 v[148:151], v134 offset:1024
	ds_read_b128 v[152:155], v134 offset:2048
	ds_read_b128 v[156:159], v134 offset:3072
	v_add_u32_e32 v134, s59, v1
	ds_read_b128 v[160:163], v134
	ds_read_b128 v[164:167], v134 offset:1024
	ds_read_b128 v[168:171], v134 offset:2048
	ds_read_b128 v[172:175], v134 offset:3072
	s_add_u32 s38, s44, 0x300000
	s_addc_u32 s39, s45, 0
	s_mov_b32 m0, s53
	ds_read_b128 v[180:183], v179 offset:32768
	ds_read_b128 v[184:187], v179 offset:33792
	ds_read_b128 v[188:191], v179 offset:34816
	ds_read_b128 v[192:195], v179 offset:35840
	ds_read_b128 v[196:199], v179 offset:36864
	ds_read_b128 v[200:203], v179 offset:37888
	ds_read_b128 v[204:207], v179 offset:38912
	ds_read_b128 v[208:211], v179 offset:39936
	global_load_lds_dwordx4 v130, s[38:39]
	s_mov_b32 m0, s54
	s_nop 0
	global_load_lds_dwordx4 v132, s[38:39]
	s_waitcnt vmcnt(8)
	s_waitcnt lgkmcnt(0)
	s_barrier
	s_waitcnt lgkmcnt(0)
	v_mfma_f32_16x16x32_bf16 v[126:129], v[144:147], v[180:183], v[126:129]
	v_mfma_f32_16x16x32_bf16 v[126:129], v[148:151], v[184:187], v[126:129]
	v_mfma_f32_16x16x32_bf16 v[122:125], v[152:155], v[180:183], v[122:125]
	v_mfma_f32_16x16x32_bf16 v[122:125], v[156:159], v[184:187], v[122:125]
	v_mfma_f32_16x16x32_bf16 v[110:113], v[144:147], v[188:191], v[110:113]
	v_mfma_f32_16x16x32_bf16 v[110:113], v[148:151], v[192:195], v[110:113]
	v_mfma_f32_16x16x32_bf16 v[106:109], v[152:155], v[188:191], v[106:109]
	v_mfma_f32_16x16x32_bf16 v[106:109], v[156:159], v[192:195], v[106:109]
	v_mfma_f32_16x16x32_bf16 v[94:97], v[144:147], v[196:199], v[94:97]
	v_mfma_f32_16x16x32_bf16 v[94:97], v[148:151], v[200:203], v[94:97]
	v_mfma_f32_16x16x32_bf16 v[90:93], v[152:155], v[196:199], v[90:93]
	v_mfma_f32_16x16x32_bf16 v[90:93], v[156:159], v[200:203], v[90:93]
	v_mfma_f32_16x16x32_bf16 v[78:81], v[144:147], v[204:207], v[78:81]
	v_mfma_f32_16x16x32_bf16 v[78:81], v[148:151], v[208:211], v[78:81]
	v_mfma_f32_16x16x32_bf16 v[74:77], v[152:155], v[204:207], v[74:77]
	v_mfma_f32_16x16x32_bf16 v[74:77], v[156:159], v[208:211], v[74:77]
	v_mfma_f32_16x16x32_bf16 v[118:121], v[160:163], v[180:183], v[118:121]
	v_mfma_f32_16x16x32_bf16 v[118:121], v[164:167], v[184:187], v[118:121]
	v_mfma_f32_16x16x32_bf16 v[114:117], v[168:171], v[180:183], v[114:117]
	v_mfma_f32_16x16x32_bf16 v[114:117], v[172:175], v[184:187], v[114:117]
	v_mfma_f32_16x16x32_bf16 v[102:105], v[160:163], v[188:191], v[102:105]
	v_mfma_f32_16x16x32_bf16 v[102:105], v[164:167], v[192:195], v[102:105]
	v_mfma_f32_16x16x32_bf16 v[98:101], v[168:171], v[188:191], v[98:101]
	v_mfma_f32_16x16x32_bf16 v[98:101], v[172:175], v[192:195], v[98:101]
	v_mfma_f32_16x16x32_bf16 v[86:89], v[160:163], v[196:199], v[86:89]
	v_mfma_f32_16x16x32_bf16 v[86:89], v[164:167], v[200:203], v[86:89]
	v_mfma_f32_16x16x32_bf16 v[82:85], v[168:171], v[196:199], v[82:85]
	v_mfma_f32_16x16x32_bf16 v[82:85], v[172:175], v[200:203], v[82:85]
	v_mfma_f32_16x16x32_bf16 v[70:73], v[160:163], v[204:207], v[70:73]
	v_mfma_f32_16x16x32_bf16 v[70:73], v[164:167], v[208:211], v[70:73]
	v_mfma_f32_16x16x32_bf16 v[66:69], v[168:171], v[204:207], v[66:69]
	v_mfma_f32_16x16x32_bf16 v[66:69], v[172:175], v[208:211], v[66:69]
	s_barrier
	s_add_i32 s38, s58, s50
	s_add_u32 s98, s42, 0x80
	s_addc_u32 s99, s43, 0
	s_add_u32 s100, s44, 0x80
	s_addc_u32 s101, s45, 0
	s_mov_b32 m0, s38
	ds_read_b128 v[180:183], v179 offset:49152
	ds_read_b128 v[184:187], v179 offset:50176
	ds_read_b128 v[188:191], v179 offset:51200
	ds_read_b128 v[192:195], v179 offset:52224
	ds_read_b128 v[196:199], v179 offset:53248
	ds_read_b128 v[200:203], v179 offset:54272
	ds_read_b128 v[204:207], v179 offset:55296
	ds_read_b128 v[208:211], v179 offset:56320
	global_load_lds_dwordx4 v130, s[98:99]
	s_add_i32 m0, s38, 0x2000
	s_add_u32 s38, s42, 0x300080
	s_addc_u32 s39, s43, 0
	s_add_i32 s42, s59, s50
	global_load_lds_dwordx4 v132, s[98:99]
	s_mov_b32 m0, s42
	s_nop 0
	global_load_lds_dwordx4 v130, s[38:39]
	s_add_i32 m0, s42, 0x2000
	s_nop 0
	global_load_lds_dwordx4 v132, s[38:39]
	s_mov_b32 m0, s57
	s_nop 0
	global_load_lds_dwordx4 v130, s[100:101]
	s_mov_b32 m0, s60
	s_nop 0
	global_load_lds_dwordx4 v132, s[100:101]
	s_waitcnt vmcnt(8)
	s_waitcnt lgkmcnt(0)
	s_barrier
	s_waitcnt lgkmcnt(0)
	v_mfma_f32_16x16x32_bf16 v[62:65], v[144:147], v[180:183], v[62:65]
	v_mfma_f32_16x16x32_bf16 v[62:65], v[148:151], v[184:187], v[62:65]
	v_mfma_f32_16x16x32_bf16 v[58:61], v[152:155], v[180:183], v[58:61]
	v_mfma_f32_16x16x32_bf16 v[58:61], v[156:159], v[184:187], v[58:61]
	v_mfma_f32_16x16x32_bf16 v[46:49], v[144:147], v[188:191], v[46:49]
	v_mfma_f32_16x16x32_bf16 v[46:49], v[148:151], v[192:195], v[46:49]
	v_mfma_f32_16x16x32_bf16 v[42:45], v[152:155], v[188:191], v[42:45]
	v_mfma_f32_16x16x32_bf16 v[42:45], v[156:159], v[192:195], v[42:45]
	v_mfma_f32_16x16x32_bf16 v[30:33], v[144:147], v[196:199], v[30:33]
	v_mfma_f32_16x16x32_bf16 v[30:33], v[148:151], v[200:203], v[30:33]
	v_mfma_f32_16x16x32_bf16 v[26:29], v[152:155], v[196:199], v[26:29]
	v_mfma_f32_16x16x32_bf16 v[26:29], v[156:159], v[200:203], v[26:29]
	v_mfma_f32_16x16x32_bf16 v[14:17], v[144:147], v[204:207], v[14:17]
	v_mfma_f32_16x16x32_bf16 v[14:17], v[148:151], v[208:211], v[14:17]
	v_mfma_f32_16x16x32_bf16 v[10:13], v[152:155], v[204:207], v[10:13]
	v_mfma_f32_16x16x32_bf16 v[10:13], v[156:159], v[208:211], v[10:13]
	v_mfma_f32_16x16x32_bf16 v[54:57], v[160:163], v[180:183], v[54:57]
	v_mfma_f32_16x16x32_bf16 v[54:57], v[164:167], v[184:187], v[54:57]
	v_mfma_f32_16x16x32_bf16 v[50:53], v[168:171], v[180:183], v[50:53]
	v_mfma_f32_16x16x32_bf16 v[50:53], v[172:175], v[184:187], v[50:53]
	v_mfma_f32_16x16x32_bf16 v[38:41], v[160:163], v[188:191], v[38:41]
	v_mfma_f32_16x16x32_bf16 v[38:41], v[164:167], v[192:195], v[38:41]
	v_mfma_f32_16x16x32_bf16 v[34:37], v[168:171], v[188:191], v[34:37]
	v_mfma_f32_16x16x32_bf16 v[34:37], v[172:175], v[192:195], v[34:37]
	v_mfma_f32_16x16x32_bf16 v[22:25], v[160:163], v[196:199], v[22:25]
	v_mfma_f32_16x16x32_bf16 v[22:25], v[164:167], v[200:203], v[22:25]
	v_mfma_f32_16x16x32_bf16 v[18:21], v[168:171], v[196:199], v[18:21]
	v_mfma_f32_16x16x32_bf16 v[18:21], v[172:175], v[200:203], v[18:21]
	v_mfma_f32_16x16x32_bf16 v[6:9], v[160:163], v[204:207], v[6:9]
	v_mfma_f32_16x16x32_bf16 v[6:9], v[164:167], v[208:211], v[6:9]
	v_mfma_f32_16x16x32_bf16 v[2:5], v[168:171], v[204:207], v[2:5]
	v_mfma_f32_16x16x32_bf16 v[2:5], v[172:175], v[208:211], v[2:5]
	s_barrier
	s_add_i32 s42, s71, 2
	s_add_u32 s31, s31, 0x100
	s_addc_u32 s70, s70, 0
	s_cmp_ge_i32 s71, s69
	s_mov_b64 s[38:39], s[40:41]
	s_mov_b32 s71, s42
	s_cbranch_scc0 .LBB0_3522
	s_and_b64 vcc, exec, s[20:21]
	s_cbranch_vccz .LBB0_3543
	s_barrier
	v_lshl_or_b32 v144, s5, 8, v176
	s_cmpk_eq_i32 s69, 0xc0
	s_mov_b64 s[38:39], -1
	s_cbranch_scc0 .LBB0_3544

; #define PG8_WAIT_V(n) asm volatile("s_waitcnt vmcnt(" #n ")" ::: "memory")
; #define PG8_BAR __builtin_amdgcn_s_barrier()
; template <class Epi, class Sched, bool ALIGN_EPI = false, bool SP2 = false>
; __device__ __forceinline__ void gemm_phase(PG8_LAS unsigned char* lds, const Gemm g, const Sched& S, const Epi& E) {
;     ...
;     PG8_WAIT_V(0);
;     if constexpr (!ALIGN_EPI) { if (wr == 0) PG8_BAR; }
;     PG8_BAR;
; __device__ __forceinline__ void xcd_barrier(const XcdBarrier& b) {
;     asm volatile("s_waitcnt vmcnt(0)" ::: "memory");
;     __syncthreads();
;     if (threadIdx.x == 0) {
;         unsigned* bar = b.bar;
;         __builtin_amdgcn_s_waitcnt(0);
;         unsigned nloc = b.st[0], nx = b.st[1];
;         if (nloc == 0u) { xcd_barrier_complete(bar, b.x, nloc, nx); b.st[0] = nloc; b.st[1] = nx; }
.LBB0_3552:
	s_waitcnt vmcnt(0)
	v_readlane_b32 s2, v255, 7
	v_readlane_b32 s3, v255, 8
	s_waitcnt vmcnt(0)
	s_setprio 0
	s_barrier
	s_and_saveexec_b64 s[0:1], s[2:3]
	s_xor_b64 s[2:3], exec, s[0:1]
	s_cbranch_execz .LBB0_3605
	s_add_i32 s0, 0, 0x24020
	v_mov_b32_e32 v1, s0
	s_waitcnt vmcnt(0) expcnt(0) lgkmcnt(0)
	ds_read_b32 v3, v1
	s_add_i32 s0, 0, 0x24024
	v_mov_b32_e32 v1, s0
	ds_read_b32 v1, v1
	s_waitcnt lgkmcnt(1)
	v_cmp_ne_u32_e32 vcc, 0, v3
	s_cbranch_vccnz .LBB0_3568
	v_readlane_b32 s4, v255, 2
	v_readlane_b32 s5, v255, 3
	v_readlane_b32 s38, v255, 0
	s_load_dwordx2 s[0:1], s[4:5], 0x4
	v_readlane_b32 s39, v255, 1
	s_add_u32 s4, s38, 0x4200
	s_addc_u32 s5, s39, 0
	s_add_u32 s6, s38, 0x4400
	s_addc_u32 s7, s39, 0
	s_add_u32 s8, s38, 0x4500
	s_addc_u32 s9, s39, 0
	s_add_u32 s10, s38, 0x4600
	s_addc_u32 s11, s39, 0
	s_add_u32 s12, s38, 0x4700
	s_addc_u32 s13, s39, 0
	s_add_u32 s14, s38, 0x4800
	s_addc_u32 s15, s39, 0
	s_add_u32 s16, s38, 0x4900
	s_addc_u32 s17, s39, 0
	s_add_u32 s18, s38, 0x4a00
	s_addc_u32 s19, s39, 0
	s_add_u32 s20, s38, 0x4b00
	s_addc_u32 s21, s39, 0
	s_add_u32 s22, s38, 0x4c00
	s_addc_u32 s23, s39, 0
	s_add_u32 s24, s38, 0x4d00
	s_addc_u32 s25, s39, 0
	s_add_u32 s26, s38, 0x4e00
	s_addc_u32 s27, s39, 0
	s_add_u32 s28, s38, 0x4f00
	s_addc_u32 s29, s39, 0
	s_add_u32 s30, s38, 0x5000
	s_addc_u32 s31, s39, 0
	s_add_u32 s34, s38, 0x5100
	s_addc_u32 s35, s39, 0
	s_add_u32 s36, s38, 0x5200
	s_addc_u32 s37, s39, 0
	s_waitcnt lgkmcnt(0)
	s_mul_i32 s0, s0, s33
	s_add_u32 s38, s38, 0x5300
	s_mul_i32 s0, s0, s1
	s_addc_u32 s39, s39, 0
	s_mov_b32 s1, 1
	v_mov_b32_e32 v17, 0
	s_branch .LBB0_3556
